# fused-up epilogue: all 8 row groups now use merged 16-byte stores (m=0 groups under their row mask), 5 spare VGPRs v251-255 taken into use
# speedup vs baseline: 1.0939x; 1.0036x over previous
.LBB0_491:
	s_lshl_b32 s57, s64, 8
	s_add_i32 s57, s57, s87
	v_or_b32_e32 v156, s57, v215
	v_ashrrev_i32_e32 v157, 31, v156
	v_or_b32_e32 v174, 16, v156
	v_or_b32_e32 v172, 32, v156
	v_or_b32_e32 v170, 48, v156
	v_lshlrev_b64 v[146:147], 6, v[156:157]
	v_ashrrev_i32_e32 v175, 31, v174
	v_ashrrev_i32_e32 v173, 31, v172
	v_ashrrev_i32_e32 v171, 31, v170
	v_lshl_add_u64 v[154:155], v[136:137], 0, v[146:147]
	v_lshlrev_b64 v[146:147], 6, v[174:175]
	v_lshlrev_b64 v[158:159], 6, v[172:173]
	v_lshlrev_b64 v[162:163], 6, v[170:171]
	v_lshl_add_u64 v[150:151], v[136:137], 0, v[146:147]
	v_lshl_add_u64 v[158:159], v[136:137], 0, v[158:159]
	v_lshl_add_u64 v[162:163], v[136:137], 0, v[162:163]
	global_load_dwordx4 v[146:149], v[154:155], off
	s_nop 0
	global_load_dwordx4 v[150:153], v[150:151], off
	s_waitcnt vmcnt(0)
	v_mov_b32_e32 v166, v147
	global_load_dwordx4 v[158:161], v[158:159], off
	v_mov_b32_e32 v167, v148
	global_load_dwordx4 v[162:165], v[162:163], off
	v_mov_b32_e32 v147, v149
	v_pk_add_f32 v[146:147], v[166:167], v[146:147]
	v_mov_b32_e32 v148, v151
	v_mov_b32_e32 v149, v152
	v_mov_b32_e32 v151, v153
	v_add_f32_e32 v157, v146, v147
	v_pk_add_f32 v[146:147], v[148:149], v[150:151]
	s_waitcnt vmcnt(1)
	v_mov_b32_e32 v152, v159
	v_mov_b32_e32 v153, v160
	v_mov_b32_e32 v159, v161
	s_waitcnt vmcnt(0)
	v_mov_b32_e32 v160, v163
	v_mov_b32_e32 v161, v164
	v_mov_b32_e32 v163, v165
	v_pk_add_f32 v[148:149], v[152:153], v[158:159]
	v_pk_add_f32 v[150:151], v[160:161], v[162:163]
	v_add_f32_e32 v146, v146, v147
	v_add_f32_e32 v147, v148, v149
	v_add_f32_e32 v148, v150, v151
	ds_bpermute_b32 v152, v217, v157
	ds_bpermute_b32 v149, v217, v146
	ds_bpermute_b32 v150, v217, v147
	ds_bpermute_b32 v151, v217, v148
	s_waitcnt lgkmcnt(3)
	v_add_f32_e32 v152, v157, v152
	s_waitcnt lgkmcnt(2)
	v_add_f32_e32 v146, v146, v149
	s_waitcnt lgkmcnt(1)
	v_add_f32_e32 v147, v147, v150
	s_waitcnt lgkmcnt(0)
	v_add_f32_e32 v148, v148, v151
	ds_bpermute_b32 v153, v218, v152
	ds_bpermute_b32 v149, v218, v146
	ds_bpermute_b32 v150, v218, v147
	ds_bpermute_b32 v151, v218, v148
	s_waitcnt lgkmcnt(3)
	v_add_f32_e32 v152, v152, v153
	s_waitcnt lgkmcnt(2)
	v_add_f32_e32 v146, v146, v149
	s_waitcnt lgkmcnt(1)
	v_add_f32_e32 v147, v147, v150
	s_waitcnt lgkmcnt(0)
	v_add_f32_e32 v148, v148, v151
	v_fmamk_f32 v152, v152, 0x3a800000, v223
	v_fmamk_f32 v146, v146, 0x3a800000, v223
	v_fmamk_f32 v147, v147, 0x3a800000, v223
	v_fmamk_f32 v148, v148, 0x3a800000, v223
	v_rsq_f32_e32 v168, v152
	v_rsq_f32_e32 v162, v146
	v_rsq_f32_e32 v160, v147
	v_rsq_f32_e32 v158, v148
	v_add_co_u32_e32 v154, vcc, s81, v154
	s_nop 1
	v_addc_co_u32_e32 v155, vcc, 0, v155, vcc
	global_load_dwordx4 v[146:149], v[154:155], off
	global_load_dwordx4 v[150:153], v[154:155], off offset:1024
	global_load_dwordx4 v[164:167], v[154:155], off offset:2048
	global_load_dwordx4 v[176:179], v[154:155], off offset:3072
	s_waitcnt vmcnt(3)
	v_mov_b32_e32 v154, v147
	v_mov_b32_e32 v155, v148
	v_mov_b32_e32 v147, v149
	s_waitcnt vmcnt(2)
	v_mov_b32_e32 v148, v151
	v_mov_b32_e32 v149, v152
	v_mov_b32_e32 v151, v153
	s_waitcnt vmcnt(1)
	v_mov_b32_e32 v152, v165
	v_mov_b32_e32 v153, v166
	v_mov_b32_e32 v165, v167
	s_waitcnt vmcnt(0)
	v_mov_b32_e32 v166, v177
	v_mov_b32_e32 v167, v178
	v_mov_b32_e32 v177, v179
	v_pk_add_f32 v[146:147], v[154:155], v[146:147]
	v_pk_add_f32 v[148:149], v[148:149], v[150:151]
	v_pk_add_f32 v[150:151], v[152:153], v[164:165]
	v_pk_add_f32 v[152:153], v[166:167], v[176:177]
	v_add_f32_e32 v146, v146, v147
	v_add_f32_e32 v147, v148, v149
	v_add_f32_e32 v148, v150, v151
	v_add_f32_e32 v149, v152, v153
	ds_bpermute_b32 v150, v217, v146
	ds_bpermute_b32 v151, v217, v147
	ds_bpermute_b32 v152, v217, v148
	ds_bpermute_b32 v153, v217, v149
	s_waitcnt lgkmcnt(3)
	v_add_f32_e32 v146, v146, v150
	s_waitcnt lgkmcnt(2)
	v_add_f32_e32 v147, v147, v151
	s_waitcnt lgkmcnt(1)
	v_add_f32_e32 v148, v148, v152
	s_waitcnt lgkmcnt(0)
	v_add_f32_e32 v149, v149, v153
	ds_bpermute_b32 v150, v218, v146
	ds_bpermute_b32 v151, v218, v147
	ds_bpermute_b32 v152, v218, v148
	ds_bpermute_b32 v153, v218, v149
	s_waitcnt lgkmcnt(3)
	v_add_f32_e32 v146, v146, v150
	s_waitcnt lgkmcnt(2)
	v_add_f32_e32 v147, v147, v151
	s_waitcnt lgkmcnt(1)
	v_add_f32_e32 v148, v148, v152
	s_waitcnt lgkmcnt(0)
	v_add_f32_e32 v149, v149, v153
	v_fmamk_f32 v146, v146, 0x3a800000, v223
	v_fmamk_f32 v147, v147, 0x3a800000, v223
	v_fmamk_f32 v148, v148, 0x3a800000, v223
	v_fmamk_f32 v149, v149, 0x3a800000, v223
	v_rsq_f32_e32 v154, v146
	v_rsq_f32_e32 v152, v147
	v_rsq_f32_e32 v150, v148
	v_rsq_f32_e32 v148, v149
	v_lshl_or_b32 v146, s62, 7, v219
	v_ashrrev_i32_e32 v147, 31, v146
	v_lshlrev_b64 v[176:177], 2, v[146:147]
	v_lshl_add_u64 v[164:165], s[10:11], 0, v[176:177]
	v_lshl_add_u64 v[178:179], s[16:17], 0, v[176:177]
	v_lshl_add_u64 v[180:181], s[24:25], 0, v[176:177]
	v_lshl_add_u64 v[166:167], s[12:13], 0, v[176:177]
	global_load_dwordx2 v[200:201], v[164:165], off
	global_load_dwordx2 v[208:209], v[166:167], off
	v_lshl_add_u64 v[182:183], s[26:27], 0, v[176:177]
	v_lshl_add_u64 v[184:185], s[28:29], 0, v[176:177]
	global_load_dwordx2 v[212:213], v[178:179], off
	global_load_dwordx2 v[210:211], v[180:181], off
	s_nop 0
	global_load_dwordx2 v[180:181], v[182:183], off
	global_load_dwordx2 v[206:207], v[184:185], off
	v_lshl_add_u64 v[178:179], s[30:31], 0, v[176:177]
	v_lshl_add_u64 v[176:177], s[52:53], 0, v[176:177]
	global_load_dwordx2 v[202:203], v[178:179], off
	global_load_dwordx2 v[204:205], v[176:177], off
	v_pk_mul_f32 v[126:127], v[126:127], v[168:169] op_sel_hi:[1,0]
	v_pk_mul_f32 v[124:125], v[124:125], v[168:169] op_sel_hi:[1,0]
	v_pk_mul_f32 v[122:123], v[122:123], v[168:169] op_sel_hi:[1,0]
	v_pk_mul_f32 v[120:121], v[120:121], v[168:169] op_sel_hi:[1,0]
	v_pk_mul_f32 v[184:185], v[116:117], v[162:163] op_sel_hi:[1,0]
	v_pk_mul_f32 v[186:187], v[104:105], v[162:163] op_sel_hi:[1,0]
	v_pk_mul_f32 v[182:183], v[112:113], v[160:161] op_sel_hi:[1,0]
	v_pk_mul_f32 v[176:177], v[100:101], v[160:161] op_sel_hi:[1,0]
	v_pk_mul_f32 v[100:101], v[108:109], v[158:159] op_sel_hi:[1,0]
	v_pk_mul_f32 v[96:97], v[96:97], v[158:159] op_sel_hi:[1,0]
	v_pk_mul_f32 v[92:93], v[92:93], v[154:155] op_sel_hi:[1,0]
	v_pk_mul_f32 v[88:89], v[88:89], v[154:155] op_sel_hi:[1,0]
	v_pk_mul_f32 v[116:117], v[84:85], v[152:153] op_sel_hi:[1,0]
	v_pk_mul_f32 v[84:85], v[68:69], v[150:151] op_sel_hi:[1,0]
	v_pk_mul_f32 v[68:69], v[76:77], v[148:149] op_sel_hi:[1,0]
	v_pk_mul_f32 v[64:65], v[64:65], v[148:149] op_sel_hi:[1,0]
	v_pk_mul_f32 v[112:113], v[72:73], v[152:153] op_sel_hi:[1,0]
	v_pk_mul_f32 v[104:105], v[80:81], v[150:151] op_sel_hi:[1,0]
	s_waitcnt vmcnt(5)
	v_mul_f32_dpp v73, v124, v212 row_shr:1 row_mask:0xf bank_mask:0xf bound_ctrl:1
	v_mov_b32_dpp v72, v124 row_shr:2 row_mask:0xf bank_mask:0xf bound_ctrl:1
	s_waitcnt vmcnt(4)
	v_fmac_f32_e32 v73, v124, v210
	v_fmac_f32_e32 v73, v200, v72
	v_add_f32_e32 v72, v208, v73
	v_mul_f32_e32 v73, 0xbfb8aa3b, v72
	v_exp_f32_e32 v73, v73
	s_waitcnt vmcnt(2)
	v_mul_f32_dpp v77, v120, v206 row_shr:1 row_mask:0xf bank_mask:0xf bound_ctrl:1
	v_mov_b32_dpp v76, v120 row_shr:2 row_mask:0xf bank_mask:0xf bound_ctrl:1
	s_waitcnt vmcnt(1)
	v_fmac_f32_e32 v77, v120, v202
	v_add_f32_e32 v73, 1.0, v73
	v_rcp_f32_e32 v73, v73
	v_fmac_f32_e32 v77, v180, v76
	s_waitcnt vmcnt(0)
	v_add_f32_e32 v76, v204, v77
	v_mul_f32_dpp v80, v121, v207 row_shr:1 row_mask:0xf bank_mask:0xf bound_ctrl:1
	v_mul_f32_dpp v77, v125, v213 row_shr:1 row_mask:0xf bank_mask:0xf bound_ctrl:1
	v_mul_f32_e32 v72, v72, v73
	v_mov_b32_dpp v73, v125 row_shr:2 row_mask:0xf bank_mask:0xf bound_ctrl:1
	v_fmac_f32_e32 v77, v125, v211
	v_fmac_f32_e32 v77, v201, v73
	v_add_f32_e32 v73, v209, v77
	v_mul_f32_e32 v77, 0xbfb8aa3b, v73
	v_exp_f32_e32 v77, v77
	v_mul_f32_e32 v72, v76, v72
	v_mov_b32_dpp v76, v121 row_shr:2 row_mask:0xf bank_mask:0xf bound_ctrl:1
	v_fmac_f32_e32 v80, v121, v203
	v_add_f32_e32 v77, 1.0, v77
	v_rcp_f32_e32 v77, v77
	v_fmac_f32_e32 v80, v181, v76
	v_add_f32_e32 v76, v205, v80
	v_or_b32_e32 v178, 2, v146
	v_mul_f32_e32 v73, v73, v77
	v_mul_f32_e32 v73, v76, v73
	v_cvt_pk_bf16_f32 v80, v72, v73
	v_ashrrev_i32_e32 v179, 31, v178
	v_mov_b32_dpp v72, v124 row_ror:1 row_mask:0xf bank_mask:0xf bound_ctrl:1
	v_mov_b32_dpp v73, v124 row_ror:2 row_mask:0xf bank_mask:0xf bound_ctrl:1
	v_mov_b32_dpp v76, v120 row_ror:1 row_mask:0xf bank_mask:0xf bound_ctrl:1
	v_mov_b32_dpp v72, v184 row_shr:1 row_mask:0xf bank_mask:0xf
	v_mul_f32_e32 v72, v212, v72
	v_mov_b32_dpp v73, v184 row_shr:2 row_mask:0xf bank_mask:0xf
	v_fmac_f32_e32 v72, v184, v210
	v_fmac_f32_e32 v72, v200, v73
	v_add_f32_e32 v72, v208, v72
	v_mul_f32_e32 v73, 0xbfb8aa3b, v72
	v_exp_f32_e32 v73, v73
	v_mov_b32_dpp v76, v186 row_shr:1 row_mask:0xf bank_mask:0xf
	v_mov_b32_dpp v77, v120 row_ror:2 row_mask:0xf bank_mask:0xf bound_ctrl:1
	v_mul_f32_e32 v76, v206, v76
	v_add_f32_e32 v73, 1.0, v73
	v_rcp_f32_e32 v73, v73
	v_mov_b32_dpp v77, v186 row_shr:2 row_mask:0xf bank_mask:0xf
	v_fmac_f32_e32 v76, v186, v202
	v_fmac_f32_e32 v76, v180, v77
	v_mul_f32_e32 v72, v72, v73
	v_mov_b32_dpp v73, v125 row_ror:1 row_mask:0xf bank_mask:0xf bound_ctrl:1
	v_add_f32_e32 v76, v204, v76
	v_mul_f32_e32 v72, v76, v72
	v_mov_b32_dpp v73, v185 row_shr:1 row_mask:0xf bank_mask:0xf
	v_mov_b32_dpp v76, v125 row_ror:2 row_mask:0xf bank_mask:0xf bound_ctrl:1
	v_mul_f32_e32 v73, v213, v73
	v_fmac_f32_e32 v73, v185, v211
	v_mov_b32_dpp v76, v185 row_shr:2 row_mask:0xf bank_mask:0xf
	v_fmac_f32_e32 v73, v201, v76
	v_add_f32_e32 v73, v209, v73
	v_mul_f32_e32 v76, 0xbfb8aa3b, v73
	v_exp_f32_e32 v76, v76
	v_mov_b32_dpp v77, v121 row_ror:1 row_mask:0xf bank_mask:0xf bound_ctrl:1
	v_mov_b32_dpp v81, v121 row_ror:2 row_mask:0xf bank_mask:0xf bound_ctrl:1
	v_add_f32_e32 v76, 1.0, v76
	v_mov_b32_dpp v77, v187 row_shr:1 row_mask:0xf bank_mask:0xf
	v_rcp_f32_e32 v76, v76
	v_mul_f32_e32 v77, v207, v77
	v_mov_b32_dpp v81, v187 row_shr:2 row_mask:0xf bank_mask:0xf
	v_fmac_f32_e32 v77, v187, v203
	v_fmac_f32_e32 v77, v181, v81
	v_add_f32_e32 v77, v205, v77
	v_mul_f32_e32 v73, v73, v76
	v_mul_f32_e32 v73, v77, v73
	v_cvt_pk_bf16_f32 v72, v72, v73
	s_nop 1
	v_mov_b32_dpp v73, v184 row_ror:1 row_mask:0xf bank_mask:0xf bound_ctrl:1
	v_mov_b32_dpp v76, v184 row_ror:2 row_mask:0xf bank_mask:0xf bound_ctrl:1
	v_mov_b32_dpp v77, v186 row_ror:1 row_mask:0xf bank_mask:0xf bound_ctrl:1
	v_mov_b32_dpp v73, v182 row_shr:1 row_mask:0xf bank_mask:0xf
	v_mul_f32_e32 v73, v212, v73
	v_mov_b32_dpp v76, v182 row_shr:2 row_mask:0xf bank_mask:0xf
	v_fmac_f32_e32 v73, v182, v210
	v_fmac_f32_e32 v73, v200, v76
	v_add_f32_e32 v73, v208, v73
	v_mul_f32_e32 v76, 0xbfb8aa3b, v73
	v_exp_f32_e32 v76, v76
	v_mov_b32_dpp v77, v176 row_shr:1 row_mask:0xf bank_mask:0xf
	v_mov_b32_dpp v81, v186 row_ror:2 row_mask:0xf bank_mask:0xf bound_ctrl:1
	v_mul_f32_e32 v77, v206, v77
	v_add_f32_e32 v76, 1.0, v76
	v_rcp_f32_e32 v76, v76
	v_mov_b32_dpp v81, v176 row_shr:2 row_mask:0xf bank_mask:0xf
	v_fmac_f32_e32 v77, v176, v202
	v_fmac_f32_e32 v77, v180, v81
	v_mul_f32_e32 v73, v73, v76
	v_mov_b32_dpp v76, v185 row_ror:1 row_mask:0xf bank_mask:0xf bound_ctrl:1
	v_add_f32_e32 v77, v204, v77
	v_mul_f32_e32 v73, v77, v73
	v_mov_b32_dpp v76, v183 row_shr:1 row_mask:0xf bank_mask:0xf
	v_mov_b32_dpp v77, v185 row_ror:2 row_mask:0xf bank_mask:0xf bound_ctrl:1
	v_mul_f32_e32 v76, v213, v76
	v_fmac_f32_e32 v76, v183, v211
	v_mov_b32_dpp v77, v183 row_shr:2 row_mask:0xf bank_mask:0xf
	v_fmac_f32_e32 v76, v201, v77
	v_add_f32_e32 v76, v209, v76
	v_mul_f32_e32 v77, 0xbfb8aa3b, v76
	v_exp_f32_e32 v77, v77
	v_mov_b32_dpp v81, v187 row_ror:1 row_mask:0xf bank_mask:0xf bound_ctrl:1
	v_mov_b32_dpp v108, v187 row_ror:2 row_mask:0xf bank_mask:0xf bound_ctrl:1
	v_add_f32_e32 v77, 1.0, v77
	v_mov_b32_dpp v81, v177 row_shr:1 row_mask:0xf bank_mask:0xf
	v_rcp_f32_e32 v77, v77
	v_mul_f32_e32 v81, v207, v81
	v_mov_b32_dpp v108, v177 row_shr:2 row_mask:0xf bank_mask:0xf
	v_fmac_f32_e32 v81, v177, v203
	v_fmac_f32_e32 v81, v181, v108
	v_add_f32_e32 v81, v205, v81
	v_mul_f32_e32 v76, v76, v77
	v_mul_f32_e32 v76, v81, v76
	v_cvt_pk_bf16_f32 v76, v73, v76
	v_mov_b32_dpp v73, v182 row_ror:1 row_mask:0xf bank_mask:0xf bound_ctrl:1
	v_mov_b32_dpp v77, v182 row_ror:2 row_mask:0xf bank_mask:0xf bound_ctrl:1
	v_mov_b32_dpp v81, v176 row_ror:1 row_mask:0xf bank_mask:0xf bound_ctrl:1
	v_mov_b32_dpp v73, v100 row_shr:1 row_mask:0xf bank_mask:0xf
	v_mul_f32_e32 v73, v212, v73
	v_mov_b32_dpp v77, v100 row_shr:2 row_mask:0xf bank_mask:0xf
	v_fmac_f32_e32 v73, v100, v210
	v_fmac_f32_e32 v73, v200, v77
	v_add_f32_e32 v73, v208, v73
	v_mul_f32_e32 v77, 0xbfb8aa3b, v73
	v_exp_f32_e32 v77, v77
	v_mov_b32_dpp v81, v96 row_shr:1 row_mask:0xf bank_mask:0xf
	v_mov_b32_dpp v108, v176 row_ror:2 row_mask:0xf bank_mask:0xf bound_ctrl:1
	v_mul_f32_e32 v81, v206, v81
	v_add_f32_e32 v77, 1.0, v77
	v_rcp_f32_e32 v77, v77
	v_mov_b32_dpp v108, v96 row_shr:2 row_mask:0xf bank_mask:0xf
	v_fmac_f32_e32 v81, v96, v202
	v_fmac_f32_e32 v81, v180, v108
	v_mul_f32_e32 v73, v73, v77
	v_mov_b32_dpp v77, v183 row_ror:1 row_mask:0xf bank_mask:0xf bound_ctrl:1
	v_add_f32_e32 v81, v204, v81
	v_mul_f32_e32 v73, v81, v73
	v_mov_b32_dpp v77, v101 row_shr:1 row_mask:0xf bank_mask:0xf
	v_mov_b32_dpp v81, v183 row_ror:2 row_mask:0xf bank_mask:0xf bound_ctrl:1
	v_mul_f32_e32 v77, v213, v77
	v_fmac_f32_e32 v77, v101, v211
	v_mov_b32_dpp v81, v101 row_shr:2 row_mask:0xf bank_mask:0xf
	v_fmac_f32_e32 v77, v201, v81
	v_add_f32_e32 v77, v209, v77
	v_mul_f32_e32 v81, 0xbfb8aa3b, v77
	v_exp_f32_e32 v81, v81
	v_mov_b32_dpp v108, v177 row_ror:1 row_mask:0xf bank_mask:0xf bound_ctrl:1
	v_mov_b32_dpp v109, v177 row_ror:2 row_mask:0xf bank_mask:0xf bound_ctrl:1
	v_add_f32_e32 v81, 1.0, v81
	v_mov_b32_dpp v108, v97 row_shr:1 row_mask:0xf bank_mask:0xf
	v_rcp_f32_e32 v81, v81
	v_mul_f32_e32 v108, v207, v108
	v_mov_b32_dpp v109, v97 row_shr:2 row_mask:0xf bank_mask:0xf
	v_fmac_f32_e32 v108, v97, v203
	v_fmac_f32_e32 v108, v181, v109
	v_add_f32_e32 v108, v205, v108
	v_mul_f32_e32 v77, v77, v81
	v_mul_f32_e32 v77, v108, v77
	v_cvt_pk_bf16_f32 v108, v73, v77
	v_lshlrev_b64 v[176:177], 2, v[178:179]
	v_lshl_add_u64 v[178:179], s[16:17], 0, v[176:177]
	v_lshl_add_u64 v[182:183], s[24:25], 0, v[176:177]
	global_load_dwordx2 v[184:185], v[164:165], off offset:8
	global_load_dwordx2 v[192:193], v[166:167], off offset:8
	v_lshl_add_u64 v[186:187], s[26:27], 0, v[176:177]
	v_lshl_add_u64 v[188:189], s[28:29], 0, v[176:177]
	global_load_dwordx2 v[196:197], v[178:179], off
	global_load_dwordx2 v[194:195], v[182:183], off
	s_nop 0
	global_load_dwordx2 v[182:183], v[186:187], off
	global_load_dwordx2 v[190:191], v[188:189], off
	v_lshl_add_u64 v[178:179], s[30:31], 0, v[176:177]
	v_lshl_add_u64 v[176:177], s[52:53], 0, v[176:177]
	global_load_dwordx2 v[186:187], v[178:179], off
	global_load_dwordx2 v[188:189], v[176:177], off
	v_mul_f32_dpp v77, v92, v212 row_shr:1 row_mask:0xf bank_mask:0xf bound_ctrl:1
	v_mov_b32_dpp v73, v92 row_shr:2 row_mask:0xf bank_mask:0xf bound_ctrl:1
	v_fmac_f32_e32 v77, v92, v210
	v_fmac_f32_e32 v77, v200, v73
	v_add_f32_e32 v73, v208, v77
	v_mul_f32_e32 v77, 0xbfb8aa3b, v73
	v_exp_f32_e32 v77, v77
	v_mul_f32_dpp v109, v88, v206 row_shr:1 row_mask:0xf bank_mask:0xf bound_ctrl:1
	v_mov_b32_dpp v81, v88 row_shr:2 row_mask:0xf bank_mask:0xf bound_ctrl:1
	v_fmac_f32_e32 v109, v88, v202
	v_add_f32_e32 v77, 1.0, v77
	v_rcp_f32_e32 v77, v77
	v_fmac_f32_e32 v109, v180, v81
	v_add_f32_e32 v81, v204, v109
	v_mul_f32_dpp v149, v89, v207 row_shr:1 row_mask:0xf bank_mask:0xf bound_ctrl:1
	v_mul_f32_dpp v109, v93, v213 row_shr:1 row_mask:0xf bank_mask:0xf bound_ctrl:1
	v_mul_f32_e32 v73, v73, v77
	v_mov_b32_dpp v77, v93 row_shr:2 row_mask:0xf bank_mask:0xf bound_ctrl:1
	v_fmac_f32_e32 v109, v93, v211
	v_fmac_f32_e32 v109, v201, v77
	v_add_f32_e32 v77, v209, v109
	v_mul_f32_e32 v109, 0xbfb8aa3b, v77
	v_exp_f32_e32 v109, v109
	v_mul_f32_e32 v73, v81, v73
	v_mov_b32_dpp v81, v89 row_shr:2 row_mask:0xf bank_mask:0xf bound_ctrl:1
	v_fmac_f32_e32 v149, v89, v203
	v_add_f32_e32 v109, 1.0, v109
	v_rcp_f32_e32 v109, v109
	v_fmac_f32_e32 v149, v181, v81
	v_add_f32_e32 v81, v205, v149
	v_mul_f32_e32 v77, v77, v109
	v_mul_f32_e32 v77, v81, v77
	v_cvt_pk_bf16_f32 v198, v73, v77
	v_mov_b32_dpp v73, v92 row_ror:1 row_mask:0xf bank_mask:0xf bound_ctrl:1
	s_nop 0
	v_mov_b32_dpp v77, v92 row_ror:2 row_mask:0xf bank_mask:0xf bound_ctrl:1
	v_mov_b32_dpp v81, v88 row_ror:1 row_mask:0xf bank_mask:0xf bound_ctrl:1
	v_mov_b32_dpp v73, v116 row_shr:1 row_mask:0xf bank_mask:0xf
	v_mul_f32_e32 v73, v212, v73
	v_mov_b32_dpp v77, v116 row_shr:2 row_mask:0xf bank_mask:0xf
	v_fmac_f32_e32 v73, v210, v116
	v_fmac_f32_e32 v73, v200, v77
	v_add_f32_e32 v73, v208, v73
	v_mul_f32_e32 v77, 0xbfb8aa3b, v73
	v_exp_f32_e32 v77, v77
	v_mov_b32_dpp v81, v112 row_shr:1 row_mask:0xf bank_mask:0xf
	v_mov_b32_dpp v109, v88 row_ror:2 row_mask:0xf bank_mask:0xf bound_ctrl:1
	v_mul_f32_e32 v81, v206, v81
	v_add_f32_e32 v77, 1.0, v77
	v_rcp_f32_e32 v77, v77
	v_mov_b32_dpp v109, v112 row_shr:2 row_mask:0xf bank_mask:0xf
	v_fmac_f32_e32 v81, v112, v202
	v_fmac_f32_e32 v81, v180, v109
	v_mul_f32_e32 v73, v73, v77
	v_mov_b32_dpp v77, v93 row_ror:1 row_mask:0xf bank_mask:0xf bound_ctrl:1
	v_add_f32_e32 v81, v204, v81
	v_mul_f32_e32 v73, v81, v73
	v_mov_b32_dpp v77, v117 row_shr:1 row_mask:0xf bank_mask:0xf
	v_mov_b32_dpp v81, v93 row_ror:2 row_mask:0xf bank_mask:0xf bound_ctrl:1
	v_mul_f32_e32 v77, v213, v77
	v_fmac_f32_e32 v77, v211, v117
	v_mov_b32_dpp v81, v117 row_shr:2 row_mask:0xf bank_mask:0xf
	v_fmac_f32_e32 v77, v201, v81
	v_add_f32_e32 v77, v209, v77
	v_mul_f32_e32 v81, 0xbfb8aa3b, v77
	v_exp_f32_e32 v81, v81
	v_mov_b32_dpp v109, v89 row_ror:1 row_mask:0xf bank_mask:0xf bound_ctrl:1
	v_mov_b32_dpp v149, v89 row_ror:2 row_mask:0xf bank_mask:0xf bound_ctrl:1
	v_add_f32_e32 v81, 1.0, v81
	v_mov_b32_dpp v109, v113 row_shr:1 row_mask:0xf bank_mask:0xf
	v_rcp_f32_e32 v81, v81
	v_mul_f32_e32 v109, v207, v109
	v_mov_b32_dpp v149, v113 row_shr:2 row_mask:0xf bank_mask:0xf
	v_fmac_f32_e32 v109, v113, v203
	v_fmac_f32_e32 v109, v181, v149
	v_add_f32_e32 v109, v205, v109
	v_mul_f32_e32 v77, v77, v81
	v_mul_f32_e32 v77, v109, v77
	v_cvt_pk_bf16_f32 v176, v73, v77
	v_mov_b32_dpp v73, v116 row_ror:1 row_mask:0xf bank_mask:0xf bound_ctrl:1
	s_nop 0
	v_mov_b32_dpp v77, v116 row_ror:2 row_mask:0xf bank_mask:0xf bound_ctrl:1
	v_mov_b32_dpp v81, v112 row_ror:1 row_mask:0xf bank_mask:0xf bound_ctrl:1
	v_mov_b32_dpp v73, v104 row_shr:1 row_mask:0xf bank_mask:0xf
	v_mul_f32_e32 v73, v212, v73
	v_mov_b32_dpp v77, v104 row_shr:2 row_mask:0xf bank_mask:0xf
	v_fmac_f32_e32 v73, v210, v104
	v_fmac_f32_e32 v73, v200, v77
	v_add_f32_e32 v73, v208, v73
	v_mul_f32_e32 v77, 0xbfb8aa3b, v73
	v_exp_f32_e32 v77, v77
	v_mov_b32_dpp v81, v84 row_shr:1 row_mask:0xf bank_mask:0xf
	v_mov_b32_dpp v109, v112 row_ror:2 row_mask:0xf bank_mask:0xf bound_ctrl:1
	v_mul_f32_e32 v81, v206, v81
	v_add_f32_e32 v77, 1.0, v77
	v_rcp_f32_e32 v77, v77
	v_mov_b32_dpp v109, v84 row_shr:2 row_mask:0xf bank_mask:0xf
	v_fmac_f32_e32 v81, v84, v202
	v_fmac_f32_e32 v81, v180, v109
	v_mul_f32_e32 v73, v73, v77
	v_mov_b32_dpp v77, v117 row_ror:1 row_mask:0xf bank_mask:0xf bound_ctrl:1
	v_add_f32_e32 v81, v204, v81
	v_mul_f32_e32 v73, v81, v73
	v_mov_b32_dpp v77, v105 row_shr:1 row_mask:0xf bank_mask:0xf
	v_mov_b32_dpp v81, v117 row_ror:2 row_mask:0xf bank_mask:0xf bound_ctrl:1
	v_mul_f32_e32 v77, v213, v77
	v_fmac_f32_e32 v77, v211, v105
	v_mov_b32_dpp v81, v105 row_shr:2 row_mask:0xf bank_mask:0xf
	v_fmac_f32_e32 v77, v201, v81
	v_add_f32_e32 v77, v209, v77
	v_mul_f32_e32 v81, 0xbfb8aa3b, v77
	v_exp_f32_e32 v81, v81
	v_mov_b32_dpp v109, v113 row_ror:1 row_mask:0xf bank_mask:0xf bound_ctrl:1
	v_mov_b32_dpp v112, v113 row_ror:2 row_mask:0xf bank_mask:0xf bound_ctrl:1
	v_add_f32_e32 v81, 1.0, v81
	v_mov_b32_dpp v109, v85 row_shr:1 row_mask:0xf bank_mask:0xf
	v_rcp_f32_e32 v81, v81
	v_mul_f32_e32 v109, v207, v109
	v_mov_b32_dpp v112, v85 row_shr:2 row_mask:0xf bank_mask:0xf
	v_fmac_f32_e32 v109, v85, v203
	v_fmac_f32_e32 v109, v181, v112
	v_add_f32_e32 v109, v205, v109
	v_mul_f32_e32 v77, v77, v81
	v_mul_f32_e32 v77, v109, v77
	v_cvt_pk_bf16_f32 v178, v73, v77
	v_mov_b32_dpp v73, v104 row_ror:1 row_mask:0xf bank_mask:0xf bound_ctrl:1
	s_nop 0
	v_mov_b32_dpp v77, v104 row_ror:2 row_mask:0xf bank_mask:0xf bound_ctrl:1
	v_mov_b32_dpp v81, v84 row_ror:1 row_mask:0xf bank_mask:0xf bound_ctrl:1
	v_mov_b32_dpp v73, v68 row_shr:1 row_mask:0xf bank_mask:0xf
	v_mul_f32_e32 v73, v212, v73
	v_mov_b32_dpp v77, v68 row_shr:2 row_mask:0xf bank_mask:0xf
	v_fmac_f32_e32 v73, v210, v68
	v_fmac_f32_e32 v73, v200, v77
	v_add_f32_e32 v73, v208, v73
	v_mul_f32_e32 v77, 0xbfb8aa3b, v73
	v_exp_f32_e32 v77, v77
	v_mov_b32_dpp v81, v64 row_shr:1 row_mask:0xf bank_mask:0xf
	v_mov_b32_dpp v84, v84 row_ror:2 row_mask:0xf bank_mask:0xf bound_ctrl:1
	v_mul_f32_e32 v81, v206, v81
	v_add_f32_e32 v77, 1.0, v77
	v_rcp_f32_e32 v77, v77
	v_mov_b32_dpp v84, v64 row_shr:2 row_mask:0xf bank_mask:0xf
	v_fmac_f32_e32 v81, v202, v64
	v_fmac_f32_e32 v81, v180, v84
	v_mul_f32_e32 v73, v73, v77
	v_mov_b32_dpp v77, v105 row_ror:1 row_mask:0xf bank_mask:0xf bound_ctrl:1
	v_add_f32_e32 v81, v204, v81
	v_mul_f32_e32 v73, v81, v73
	v_mov_b32_dpp v77, v69 row_shr:1 row_mask:0xf bank_mask:0xf
	v_mov_b32_dpp v81, v105 row_ror:2 row_mask:0xf bank_mask:0xf bound_ctrl:1
	v_mul_f32_e32 v77, v213, v77
	v_fmac_f32_e32 v77, v211, v69
	v_mov_b32_dpp v81, v69 row_shr:2 row_mask:0xf bank_mask:0xf
	v_fmac_f32_e32 v77, v201, v81
	v_add_f32_e32 v77, v209, v77
	v_mul_f32_e32 v81, 0xbfb8aa3b, v77
	v_exp_f32_e32 v81, v81
	v_mov_b32_dpp v84, v85 row_ror:1 row_mask:0xf bank_mask:0xf bound_ctrl:1
	v_mov_b32_dpp v85, v85 row_ror:2 row_mask:0xf bank_mask:0xf bound_ctrl:1
	v_add_f32_e32 v81, 1.0, v81
	v_mov_b32_dpp v84, v65 row_shr:1 row_mask:0xf bank_mask:0xf
	v_rcp_f32_e32 v81, v81
	v_mul_f32_e32 v84, v207, v84
	v_mov_b32_dpp v85, v65 row_shr:2 row_mask:0xf bank_mask:0xf
	v_fmac_f32_e32 v84, v203, v65
	v_fmac_f32_e32 v84, v181, v85
	v_add_f32_e32 v84, v205, v84
	v_mul_f32_e32 v77, v77, v81
	v_mul_f32_e32 v77, v84, v77
	v_cvt_pk_bf16_f32 v180, v73, v77
	s_waitcnt vmcnt(5)
	s_nop 0
	v_mul_f32_dpp v77, v126, v196 row_shr:1 row_mask:0xf bank_mask:0xf bound_ctrl:1
	v_mov_b32_dpp v73, v126 row_shr:2 row_mask:0xf bank_mask:0xf bound_ctrl:1
	s_waitcnt vmcnt(4)
	v_fmac_f32_e32 v77, v126, v194
	v_fmac_f32_e32 v77, v184, v73
	v_add_f32_e32 v73, v192, v77
	v_mul_f32_e32 v77, 0xbfb8aa3b, v73
	v_exp_f32_e32 v77, v77
	s_waitcnt vmcnt(2)
	v_mul_f32_dpp v84, v122, v190 row_shr:1 row_mask:0xf bank_mask:0xf bound_ctrl:1
	v_mov_b32_dpp v81, v122 row_shr:2 row_mask:0xf bank_mask:0xf bound_ctrl:1
	s_waitcnt vmcnt(1)
	v_fmac_f32_e32 v84, v122, v186
	v_add_f32_e32 v77, 1.0, v77
	v_rcp_f32_e32 v77, v77
	v_fmac_f32_e32 v84, v182, v81
	s_waitcnt vmcnt(0)
	v_add_f32_e32 v81, v188, v84
	v_mul_f32_dpp v85, v123, v191 row_shr:1 row_mask:0xf bank_mask:0xf bound_ctrl:1
	v_mul_f32_dpp v84, v127, v197 row_shr:1 row_mask:0xf bank_mask:0xf bound_ctrl:1
	v_mul_f32_e32 v73, v73, v77
	v_mov_b32_dpp v77, v127 row_shr:2 row_mask:0xf bank_mask:0xf bound_ctrl:1
	v_fmac_f32_e32 v84, v127, v195
	v_fmac_f32_e32 v84, v185, v77
	v_add_f32_e32 v77, v193, v84
	v_mul_f32_e32 v84, 0xbfb8aa3b, v77
	v_exp_f32_e32 v84, v84
	v_mul_f32_e32 v73, v81, v73
	v_mov_b32_dpp v81, v123 row_shr:2 row_mask:0xf bank_mask:0xf bound_ctrl:1
	v_fmac_f32_e32 v85, v123, v187
	v_add_f32_e32 v84, 1.0, v84
	v_rcp_f32_e32 v84, v84
	v_fmac_f32_e32 v85, v183, v81
	v_add_f32_e32 v81, v189, v85
	v_mul_f32_e32 v77, v77, v84
	v_mul_f32_e32 v77, v81, v77
	v_cvt_pk_bf16_f32 v81, v73, v77
	s_and_saveexec_b64 s[62:63], s[2:3]
	s_xor_b64 s[62:63], exec, s[62:63]
	s_cbranch_execz .LBB0_493
	v_mov_b64_e32 v[84:85], s[48:49]
	v_mad_i64_i32 v[84:85], s[64:65], v156, s93, v[84:85]
	v_lshl_add_u64 v[84:85], v[146:147], 1, v[84:85]
	v_mov_b32_e32 v251, v80
	v_mov_b32_e32 v252, v81

.LBB0_498:
	s_or_b64 exec, exec, s[62:63]
	s_addk_i32 s57, 0x80
	v_or_b32_e32 v72, 16, v146
	v_pk_mul_f32 v[94:95], v[94:95], v[154:155] op_sel_hi:[1,0]
	v_pk_mul_f32 v[90:91], v[90:91], v[154:155] op_sel_hi:[1,0]
	v_or_b32_e32 v157, s57, v215
	v_ashrrev_i32_e32 v73, 31, v72
	v_lshlrev_b64 v[96:97], 2, v[72:73]
	v_lshl_add_u64 v[98:99], s[16:17], 0, v[96:97]
	v_lshl_add_u64 v[110:111], s[28:29], 0, v[96:97]
	global_load_dwordx2 v[100:101], v[164:165], off offset:64
	v_lshl_add_u64 v[102:103], s[24:25], 0, v[96:97]
	global_load_dwordx2 v[112:113], v[166:167], off offset:64
	v_lshl_add_u64 v[108:109], s[26:27], 0, v[96:97]
	global_load_dwordx2 v[116:117], v[98:99], off
	global_load_dwordx2 v[114:115], v[102:103], off
	s_nop 0
	global_load_dwordx2 v[98:99], v[108:109], off
	s_nop 0
	global_load_dwordx2 v[110:111], v[110:111], off
	v_lshl_add_u64 v[102:103], s[30:31], 0, v[96:97]
	v_lshl_add_u64 v[96:97], s[52:53], 0, v[96:97]
	global_load_dwordx2 v[102:103], v[102:103], off
	v_mul_f32_dpp v151, v90, v190 row_shr:1 row_mask:0xf bank_mask:0xf bound_ctrl:1
	global_load_dwordx2 v[108:109], v[96:97], off
	v_mul_f32_dpp v97, v94, v196 row_shr:1 row_mask:0xf bank_mask:0xf bound_ctrl:1
	v_mov_b32_dpp v96, v94 row_shr:2 row_mask:0xf bank_mask:0xf bound_ctrl:1
	v_fmac_f32_e32 v97, v94, v194
	v_fmac_f32_e32 v97, v184, v96
	v_add_f32_e32 v96, v192, v97
	v_mul_f32_e32 v97, 0xbfb8aa3b, v96
	v_exp_f32_e32 v97, v97
	v_mov_b32_dpp v149, v90 row_shr:2 row_mask:0xf bank_mask:0xf bound_ctrl:1
	v_fmac_f32_e32 v151, v90, v186
	v_fmac_f32_e32 v151, v182, v149
	v_add_f32_e32 v97, 1.0, v97
	v_rcp_f32_e32 v97, v97
	v_add_f32_e32 v149, v188, v151
	v_mul_f32_dpp v151, v95, v197 row_shr:1 row_mask:0xf bank_mask:0xf bound_ctrl:1
	v_fmac_f32_e32 v151, v95, v195
	v_mul_f32_e32 v96, v96, v97
	v_mov_b32_dpp v97, v95 row_shr:2 row_mask:0xf bank_mask:0xf bound_ctrl:1
	v_fmac_f32_e32 v151, v185, v97
	v_add_f32_e32 v97, v193, v151
	v_mul_f32_e32 v151, 0xbfb8aa3b, v97
	v_exp_f32_e32 v151, v151
	v_mul_f32_dpp v153, v91, v191 row_shr:1 row_mask:0xf bank_mask:0xf bound_ctrl:1
	v_mul_f32_e32 v96, v149, v96
	v_mov_b32_dpp v149, v91 row_shr:2 row_mask:0xf bank_mask:0xf bound_ctrl:1
	v_add_f32_e32 v151, 1.0, v151
	v_rcp_f32_e32 v151, v151
	v_fmac_f32_e32 v153, v91, v187
	v_fmac_f32_e32 v153, v183, v149
	v_add_f32_e32 v149, v189, v153
	v_mul_f32_e32 v97, v97, v151
	v_mul_f32_e32 v97, v149, v97
	v_cvt_pk_bf16_f32 v199, v96, v97
	s_and_saveexec_b64 s[62:63], s[2:3]
	s_xor_b64 s[62:63], exec, s[62:63]
	s_cbranch_execz .LBB0_500
	v_mov_b64_e32 v[96:97], s[48:49]
	v_mad_i64_i32 v[96:97], s[64:65], v157, s93, v[96:97]
	v_lshl_add_u64 v[96:97], v[146:147], 1, v[96:97]
	v_mov_b32_e32 v253, v198
	v_mov_b32_e32 v254, v199

.LBB0_505:
	s_or_b64 exec, exec, s[62:63]
	v_mov_b32_e32 v169, v168
	v_mov_b32_e32 v163, v162
	v_mov_b32_e32 v161, v160
	v_mov_b32_e32 v159, v158
	v_mov_b32_e32 v155, v154
	v_mov_b32_e32 v153, v152
	v_mov_b32_e32 v151, v150
	v_mov_b32_e32 v149, v148
	v_mov_b32_e32 v64, v168
	v_mov_b32_e32 v65, v168
	v_pk_mul_f32 v[62:63], v[62:63], v[64:65]
	v_pk_mul_f32 v[60:61], v[60:61], v[168:169]
	v_pk_mul_f32 v[58:59], v[58:59], v[64:65]
	v_pk_mul_f32 v[56:57], v[56:57], v[168:169]
	v_pk_mul_f32 v[52:53], v[52:53], v[162:163]
	v_pk_mul_f32 v[64:65], v[44:45], v[162:163]
	v_pk_mul_f32 v[48:49], v[48:49], v[160:161]
	v_pk_mul_f32 v[44:45], v[36:37], v[160:161]
	v_pk_mul_f32 v[36:37], v[40:41], v[158:159]
	v_pk_mul_f32 v[32:33], v[32:33], v[158:159]
	v_pk_mul_f32 v[28:29], v[28:29], v[154:155]
	v_pk_mul_f32 v[24:25], v[24:25], v[154:155]
	v_pk_mul_f32 v[120:121], v[20:21], v[152:153]
	v_pk_mul_f32 v[12:13], v[12:13], v[152:153]
	v_pk_mul_f32 v[20:21], v[4:5], v[150:151]
	v_pk_mul_f32 v[4:5], v[8:9], v[148:149]
	v_pk_mul_f32 v[0:1], v[0:1], v[148:149]
	v_pk_mul_f32 v[118:119], v[16:17], v[150:151]
	s_waitcnt vmcnt(4)
	v_mul_f32_dpp v16, v60, v116 row_shr:1 row_mask:0xf bank_mask:0xf bound_ctrl:1
	v_mov_b32_dpp v9, v60 row_shr:2 row_mask:0xf bank_mask:0xf bound_ctrl:1
	s_waitcnt vmcnt(3)
	v_fmac_f32_e32 v16, v60, v114
	v_fmac_f32_e32 v16, v100, v9
	v_add_f32_e32 v16, v112, v16
	v_mul_f32_e32 v9, 0xbfb8aa3b, v16
	v_exp_f32_e32 v17, v9
	s_waitcnt vmcnt(1)
	v_mul_f32_dpp v41, v56, v110 row_shr:1 row_mask:0xf bank_mask:0xf bound_ctrl:1
	v_mov_b32_dpp v40, v56 row_shr:2 row_mask:0xf bank_mask:0xf bound_ctrl:1
	s_waitcnt vmcnt(0)
	v_fmac_f32_e32 v41, v56, v102
	v_add_f32_e32 v17, 1.0, v17
	v_rcp_f32_e32 v17, v17
	v_fmac_f32_e32 v41, v98, v40
	s_waitcnt vmcnt(0)
	v_add_f32_e32 v40, v108, v41
	v_mul_f32_dpp v66, v57, v111 row_shr:1 row_mask:0xf bank_mask:0xf bound_ctrl:1
	v_mul_f32_dpp v41, v61, v117 row_shr:1 row_mask:0xf bank_mask:0xf bound_ctrl:1
	v_mul_f32_e32 v16, v16, v17
	v_mov_b32_dpp v17, v61 row_shr:2 row_mask:0xf bank_mask:0xf bound_ctrl:1
	v_fmac_f32_e32 v41, v61, v115
	v_fmac_f32_e32 v41, v101, v17
	v_add_f32_e32 v17, v113, v41
	v_mul_f32_e32 v41, 0xbfb8aa3b, v17
	v_exp_f32_e32 v41, v41
	v_mul_f32_e32 v16, v40, v16
	v_mov_b32_dpp v40, v57 row_shr:2 row_mask:0xf bank_mask:0xf bound_ctrl:1
	v_fmac_f32_e32 v66, v57, v103
	v_add_f32_e32 v41, 1.0, v41
	v_rcp_f32_e32 v41, v41
	v_fmac_f32_e32 v66, v99, v40
	v_add_f32_e32 v40, v109, v66
	v_or_b32_e32 v8, 18, v146
	v_mul_f32_e32 v17, v17, v41
	v_mul_f32_e32 v17, v40, v17
	v_cvt_pk_bf16_f32 v94, v16, v17
	v_ashrrev_i32_e32 v9, 31, v8
	v_mov_b32_dpp v16, v60 row_ror:1 row_mask:0xf bank_mask:0xf bound_ctrl:1
	v_mov_b32_dpp v17, v60 row_ror:2 row_mask:0xf bank_mask:0xf bound_ctrl:1
	v_mov_b32_dpp v40, v56 row_ror:1 row_mask:0xf bank_mask:0xf bound_ctrl:1
	v_mov_b32_dpp v16, v52 row_shr:1 row_mask:0xf bank_mask:0xf
	v_mul_f32_e32 v16, v116, v16
	v_mov_b32_dpp v17, v52 row_shr:2 row_mask:0xf bank_mask:0xf
	v_fmac_f32_e32 v16, v52, v114
	v_fmac_f32_e32 v16, v100, v17
	v_add_f32_e32 v16, v112, v16
	v_mul_f32_e32 v17, 0xbfb8aa3b, v16
	v_exp_f32_e32 v17, v17
	v_mov_b32_dpp v40, v64 row_shr:1 row_mask:0xf bank_mask:0xf
	v_mov_b32_dpp v41, v56 row_ror:2 row_mask:0xf bank_mask:0xf bound_ctrl:1
	v_mul_f32_e32 v40, v110, v40
	v_add_f32_e32 v17, 1.0, v17
	v_rcp_f32_e32 v17, v17
	v_mov_b32_dpp v41, v64 row_shr:2 row_mask:0xf bank_mask:0xf
	v_fmac_f32_e32 v40, v64, v102
	v_fmac_f32_e32 v40, v98, v41
	v_mul_f32_e32 v16, v16, v17
	v_mov_b32_dpp v17, v61 row_ror:1 row_mask:0xf bank_mask:0xf bound_ctrl:1
	v_add_f32_e32 v40, v108, v40
	v_mul_f32_e32 v16, v40, v16
	v_mov_b32_dpp v17, v53 row_shr:1 row_mask:0xf bank_mask:0xf
	v_mov_b32_dpp v40, v61 row_ror:2 row_mask:0xf bank_mask:0xf bound_ctrl:1
	v_mul_f32_e32 v17, v117, v17
	v_fmac_f32_e32 v17, v53, v115
	v_mov_b32_dpp v40, v53 row_shr:2 row_mask:0xf bank_mask:0xf
	v_fmac_f32_e32 v17, v101, v40
	v_add_f32_e32 v17, v113, v17
	v_mul_f32_e32 v40, 0xbfb8aa3b, v17
	v_exp_f32_e32 v40, v40
	v_mov_b32_dpp v41, v57 row_ror:1 row_mask:0xf bank_mask:0xf bound_ctrl:1
	v_mov_b32_dpp v66, v57 row_ror:2 row_mask:0xf bank_mask:0xf bound_ctrl:1
	v_add_f32_e32 v40, 1.0, v40
	v_mov_b32_dpp v41, v65 row_shr:1 row_mask:0xf bank_mask:0xf
	v_rcp_f32_e32 v40, v40
	v_mul_f32_e32 v41, v111, v41
	v_mov_b32_dpp v66, v65 row_shr:2 row_mask:0xf bank_mask:0xf
	v_fmac_f32_e32 v41, v65, v103
	v_fmac_f32_e32 v41, v99, v66
	v_add_f32_e32 v41, v109, v41
	v_mul_f32_e32 v17, v17, v40
	v_mul_f32_e32 v17, v41, v17
	v_cvt_pk_bf16_f32 v88, v16, v17
	v_mov_b32_dpp v16, v52 row_ror:1 row_mask:0xf bank_mask:0xf bound_ctrl:1
	s_nop 0
	v_mov_b32_dpp v17, v52 row_ror:2 row_mask:0xf bank_mask:0xf bound_ctrl:1
	v_mov_b32_dpp v40, v64 row_ror:1 row_mask:0xf bank_mask:0xf bound_ctrl:1
	v_mov_b32_dpp v16, v48 row_shr:1 row_mask:0xf bank_mask:0xf
	v_mul_f32_e32 v16, v116, v16
	v_mov_b32_dpp v17, v48 row_shr:2 row_mask:0xf bank_mask:0xf
	v_fmac_f32_e32 v16, v48, v114
	v_fmac_f32_e32 v16, v100, v17
	v_add_f32_e32 v16, v112, v16
	v_mul_f32_e32 v17, 0xbfb8aa3b, v16
	v_exp_f32_e32 v17, v17
	v_mov_b32_dpp v40, v44 row_shr:1 row_mask:0xf bank_mask:0xf
	v_mov_b32_dpp v41, v64 row_ror:2 row_mask:0xf bank_mask:0xf bound_ctrl:1
	v_mul_f32_e32 v40, v110, v40
	v_add_f32_e32 v17, 1.0, v17
	v_rcp_f32_e32 v17, v17
	v_mov_b32_dpp v41, v44 row_shr:2 row_mask:0xf bank_mask:0xf
	v_fmac_f32_e32 v40, v44, v102
	v_fmac_f32_e32 v40, v98, v41
	v_mul_f32_e32 v16, v16, v17
	v_mov_b32_dpp v17, v53 row_ror:1 row_mask:0xf bank_mask:0xf bound_ctrl:1
	v_add_f32_e32 v40, v108, v40
	v_mul_f32_e32 v16, v40, v16
	v_mov_b32_dpp v17, v49 row_shr:1 row_mask:0xf bank_mask:0xf
	v_mov_b32_dpp v40, v53 row_ror:2 row_mask:0xf bank_mask:0xf bound_ctrl:1
	v_mul_f32_e32 v17, v117, v17
	v_fmac_f32_e32 v17, v49, v115
	v_mov_b32_dpp v40, v49 row_shr:2 row_mask:0xf bank_mask:0xf
	v_fmac_f32_e32 v17, v101, v40
	v_add_f32_e32 v17, v113, v17
	v_mul_f32_e32 v40, 0xbfb8aa3b, v17
	v_exp_f32_e32 v40, v40
	v_mov_b32_dpp v41, v65 row_ror:1 row_mask:0xf bank_mask:0xf bound_ctrl:1
	v_mov_b32_dpp v52, v65 row_ror:2 row_mask:0xf bank_mask:0xf bound_ctrl:1
	v_add_f32_e32 v40, 1.0, v40
	v_mov_b32_dpp v41, v45 row_shr:1 row_mask:0xf bank_mask:0xf
	v_rcp_f32_e32 v40, v40
	v_mul_f32_e32 v41, v111, v41
	v_mov_b32_dpp v52, v45 row_shr:2 row_mask:0xf bank_mask:0xf
	v_fmac_f32_e32 v41, v45, v103
	v_fmac_f32_e32 v41, v99, v52
	v_add_f32_e32 v41, v109, v41
	v_mul_f32_e32 v17, v17, v40
	v_mul_f32_e32 v17, v41, v17
	v_cvt_pk_bf16_f32 v90, v16, v17
	v_mov_b32_dpp v16, v48 row_ror:1 row_mask:0xf bank_mask:0xf bound_ctrl:1
	s_nop 0
	v_mov_b32_dpp v17, v48 row_ror:2 row_mask:0xf bank_mask:0xf bound_ctrl:1
	v_mov_b32_dpp v40, v44 row_ror:1 row_mask:0xf bank_mask:0xf bound_ctrl:1
	v_mov_b32_dpp v16, v36 row_shr:1 row_mask:0xf bank_mask:0xf
	v_mul_f32_e32 v16, v116, v16
	v_mov_b32_dpp v17, v36 row_shr:2 row_mask:0xf bank_mask:0xf
	v_fmac_f32_e32 v16, v36, v114
	v_fmac_f32_e32 v16, v100, v17
	v_add_f32_e32 v16, v112, v16
	v_mul_f32_e32 v17, 0xbfb8aa3b, v16
	v_exp_f32_e32 v17, v17
	v_mov_b32_dpp v40, v32 row_shr:1 row_mask:0xf bank_mask:0xf
	v_mov_b32_dpp v41, v44 row_ror:2 row_mask:0xf bank_mask:0xf bound_ctrl:1
	v_mul_f32_e32 v40, v110, v40
	v_add_f32_e32 v17, 1.0, v17
	v_rcp_f32_e32 v17, v17
	v_mov_b32_dpp v41, v32 row_shr:2 row_mask:0xf bank_mask:0xf
	v_fmac_f32_e32 v40, v32, v102
	v_fmac_f32_e32 v40, v98, v41
	v_mul_f32_e32 v16, v16, v17
	v_mov_b32_dpp v17, v49 row_ror:1 row_mask:0xf bank_mask:0xf bound_ctrl:1
	v_add_f32_e32 v40, v108, v40
	v_mul_f32_e32 v16, v40, v16
	v_mov_b32_dpp v17, v37 row_shr:1 row_mask:0xf bank_mask:0xf
	v_mov_b32_dpp v40, v49 row_ror:2 row_mask:0xf bank_mask:0xf bound_ctrl:1
	v_mul_f32_e32 v17, v117, v17
	v_fmac_f32_e32 v17, v37, v115
	v_mov_b32_dpp v40, v37 row_shr:2 row_mask:0xf bank_mask:0xf
	v_fmac_f32_e32 v17, v101, v40
	v_add_f32_e32 v17, v113, v17
	v_mul_f32_e32 v40, 0xbfb8aa3b, v17
	v_exp_f32_e32 v40, v40
	v_mov_b32_dpp v41, v45 row_ror:1 row_mask:0xf bank_mask:0xf bound_ctrl:1
	v_mov_b32_dpp v44, v45 row_ror:2 row_mask:0xf bank_mask:0xf bound_ctrl:1
	v_add_f32_e32 v40, 1.0, v40
	v_mov_b32_dpp v41, v33 row_shr:1 row_mask:0xf bank_mask:0xf
	v_rcp_f32_e32 v40, v40
	v_mul_f32_e32 v41, v111, v41
	v_mov_b32_dpp v44, v33 row_shr:2 row_mask:0xf bank_mask:0xf
	v_fmac_f32_e32 v41, v33, v103
	v_fmac_f32_e32 v41, v99, v44
	v_add_f32_e32 v41, v109, v41
	v_mul_f32_e32 v17, v17, v40
	v_mul_f32_e32 v17, v41, v17
	v_cvt_pk_bf16_f32 v92, v16, v17
	v_lshlrev_b64 v[8:9], 2, v[8:9]
	v_lshl_add_u64 v[16:17], s[16:17], 0, v[8:9]
	v_lshl_add_u64 v[52:53], s[28:29], 0, v[8:9]
	global_load_dwordx2 v[40:41], v[164:165], off offset:72
	v_lshl_add_u64 v[44:45], s[24:25], 0, v[8:9]
	global_load_dwordx2 v[64:65], v[166:167], off offset:72
	v_lshl_add_u64 v[48:49], s[26:27], 0, v[8:9]
	global_load_dwordx2 v[68:69], v[16:17], off
	global_load_dwordx2 v[66:67], v[44:45], off
	s_nop 0
	global_load_dwordx2 v[16:17], v[48:49], off
	s_nop 0
	global_load_dwordx2 v[52:53], v[52:53], off
	v_lshl_add_u64 v[44:45], s[30:31], 0, v[8:9]
	v_lshl_add_u64 v[8:9], s[52:53], 0, v[8:9]
	global_load_dwordx2 v[44:45], v[44:45], off
	v_mul_f32_dpp v71, v24, v110 row_shr:1 row_mask:0xf bank_mask:0xf bound_ctrl:1
	global_load_dwordx2 v[48:49], v[8:9], off
	v_mul_f32_dpp v9, v28, v116 row_shr:1 row_mask:0xf bank_mask:0xf bound_ctrl:1
	v_mov_b32_dpp v8, v28 row_shr:2 row_mask:0xf bank_mask:0xf bound_ctrl:1
	v_fmac_f32_e32 v9, v28, v114
	v_fmac_f32_e32 v9, v100, v8
	v_add_f32_e32 v8, v112, v9
	v_mul_f32_e32 v9, 0xbfb8aa3b, v8
	v_exp_f32_e32 v9, v9
	v_mov_b32_dpp v70, v24 row_shr:2 row_mask:0xf bank_mask:0xf bound_ctrl:1
	v_fmac_f32_e32 v71, v24, v102
	v_fmac_f32_e32 v71, v98, v70
	v_add_f32_e32 v9, 1.0, v9
	v_rcp_f32_e32 v9, v9
	v_add_f32_e32 v70, v108, v71
	v_mul_f32_dpp v71, v29, v117 row_shr:1 row_mask:0xf bank_mask:0xf bound_ctrl:1
	v_fmac_f32_e32 v71, v29, v115
	v_mul_f32_e32 v8, v8, v9
	v_mov_b32_dpp v9, v29 row_shr:2 row_mask:0xf bank_mask:0xf bound_ctrl:1
	v_fmac_f32_e32 v71, v101, v9
	v_add_f32_e32 v9, v113, v71
	v_mul_f32_e32 v71, 0xbfb8aa3b, v9
	v_exp_f32_e32 v71, v71
	v_mul_f32_dpp v89, v25, v111 row_shr:1 row_mask:0xf bank_mask:0xf bound_ctrl:1
	v_mul_f32_e32 v8, v70, v8
	v_mov_b32_dpp v70, v25 row_shr:2 row_mask:0xf bank_mask:0xf bound_ctrl:1
	v_add_f32_e32 v71, 1.0, v71
	v_rcp_f32_e32 v71, v71
	v_fmac_f32_e32 v89, v25, v103
	v_fmac_f32_e32 v89, v99, v70
	v_add_f32_e32 v70, v109, v89
	v_mul_f32_e32 v9, v9, v71
	v_mul_f32_e32 v9, v70, v9
	v_cvt_pk_bf16_f32 v70, v8, v9
	v_mov_b32_dpp v8, v28 row_ror:1 row_mask:0xf bank_mask:0xf bound_ctrl:1
	s_nop 0
	v_mov_b32_dpp v9, v28 row_ror:2 row_mask:0xf bank_mask:0xf bound_ctrl:1
	v_mov_b32_dpp v71, v24 row_ror:1 row_mask:0xf bank_mask:0xf bound_ctrl:1
	v_mov_b32_dpp v8, v120 row_shr:1 row_mask:0xf bank_mask:0xf
	v_mul_f32_e32 v8, v116, v8
	v_mov_b32_dpp v9, v120 row_shr:2 row_mask:0xf bank_mask:0xf
	v_fmac_f32_e32 v8, v120, v114
	v_fmac_f32_e32 v8, v100, v9
	v_add_f32_e32 v8, v112, v8
	v_mul_f32_e32 v9, 0xbfb8aa3b, v8
	v_exp_f32_e32 v9, v9
	v_mov_b32_dpp v71, v12 row_shr:1 row_mask:0xf bank_mask:0xf
	v_mov_b32_dpp v89, v24 row_ror:2 row_mask:0xf bank_mask:0xf bound_ctrl:1
	v_mul_f32_e32 v71, v110, v71
	v_add_f32_e32 v9, 1.0, v9
	v_rcp_f32_e32 v9, v9
	v_mov_b32_dpp v89, v12 row_shr:2 row_mask:0xf bank_mask:0xf
	v_fmac_f32_e32 v71, v12, v102
	v_fmac_f32_e32 v71, v98, v89
	v_mul_f32_e32 v8, v8, v9
	v_mov_b32_dpp v9, v29 row_ror:1 row_mask:0xf bank_mask:0xf bound_ctrl:1
	v_add_f32_e32 v71, v108, v71
	v_mul_f32_e32 v8, v71, v8
	v_mov_b32_dpp v9, v121 row_shr:1 row_mask:0xf bank_mask:0xf
	v_mov_b32_dpp v71, v29 row_ror:2 row_mask:0xf bank_mask:0xf bound_ctrl:1
	v_mul_f32_e32 v9, v117, v9
	v_fmac_f32_e32 v9, v121, v115
	v_mov_b32_dpp v71, v121 row_shr:2 row_mask:0xf bank_mask:0xf
	v_fmac_f32_e32 v9, v101, v71
	v_add_f32_e32 v9, v113, v9
	v_mul_f32_e32 v71, 0xbfb8aa3b, v9
	v_exp_f32_e32 v71, v71
	v_mov_b32_dpp v89, v25 row_ror:1 row_mask:0xf bank_mask:0xf bound_ctrl:1
	v_mov_b32_dpp v91, v25 row_ror:2 row_mask:0xf bank_mask:0xf bound_ctrl:1
	v_add_f32_e32 v71, 1.0, v71
	v_mov_b32_dpp v89, v13 row_shr:1 row_mask:0xf bank_mask:0xf
	v_rcp_f32_e32 v71, v71
	v_mul_f32_e32 v89, v111, v89
	v_mov_b32_dpp v91, v13 row_shr:2 row_mask:0xf bank_mask:0xf
	v_fmac_f32_e32 v89, v13, v103
	v_fmac_f32_e32 v89, v99, v91
	v_add_f32_e32 v89, v109, v89
	v_mul_f32_e32 v9, v9, v71
	v_mul_f32_e32 v9, v89, v9
	v_cvt_pk_bf16_f32 v8, v8, v9
	s_nop 1
	v_mov_b32_dpp v9, v120 row_ror:1 row_mask:0xf bank_mask:0xf bound_ctrl:1
	v_mov_b32_dpp v71, v120 row_ror:2 row_mask:0xf bank_mask:0xf bound_ctrl:1
	v_mov_b32_dpp v89, v12 row_ror:1 row_mask:0xf bank_mask:0xf bound_ctrl:1
	v_mov_b32_dpp v9, v118 row_shr:1 row_mask:0xf bank_mask:0xf
	v_mul_f32_e32 v9, v116, v9
	v_mov_b32_dpp v71, v118 row_shr:2 row_mask:0xf bank_mask:0xf
	v_fmac_f32_e32 v9, v118, v114
	v_fmac_f32_e32 v9, v100, v71
	v_add_f32_e32 v9, v112, v9
	v_mul_f32_e32 v71, 0xbfb8aa3b, v9
	v_exp_f32_e32 v71, v71
	v_mov_b32_dpp v89, v20 row_shr:1 row_mask:0xf bank_mask:0xf
	v_mov_b32_dpp v12, v12 row_ror:2 row_mask:0xf bank_mask:0xf bound_ctrl:1
	v_mul_f32_e32 v89, v110, v89
	v_add_f32_e32 v71, 1.0, v71
	v_rcp_f32_e32 v71, v71
	v_mov_b32_dpp v12, v20 row_shr:2 row_mask:0xf bank_mask:0xf
	v_fmac_f32_e32 v89, v20, v102
	v_fmac_f32_e32 v89, v98, v12
	v_add_f32_e32 v12, v108, v89
	v_mul_f32_e32 v9, v9, v71
	v_mul_f32_e32 v9, v12, v9
	v_mov_b32_dpp v12, v121 row_ror:1 row_mask:0xf bank_mask:0xf bound_ctrl:1
	v_mov_b32_dpp v71, v121 row_ror:2 row_mask:0xf bank_mask:0xf bound_ctrl:1
	v_mov_b32_dpp v89, v13 row_ror:1 row_mask:0xf bank_mask:0xf bound_ctrl:1
	v_mov_b32_dpp v12, v119 row_shr:1 row_mask:0xf bank_mask:0xf
	v_mul_f32_e32 v12, v117, v12
	v_mov_b32_dpp v71, v119 row_shr:2 row_mask:0xf bank_mask:0xf
	v_fmac_f32_e32 v12, v119, v115
	v_fmac_f32_e32 v12, v101, v71
	v_add_f32_e32 v12, v113, v12
	v_mul_f32_e32 v71, 0xbfb8aa3b, v12
	v_exp_f32_e32 v71, v71
	v_mov_b32_dpp v89, v21 row_shr:1 row_mask:0xf bank_mask:0xf
	v_mov_b32_dpp v13, v13 row_ror:2 row_mask:0xf bank_mask:0xf bound_ctrl:1
	v_mul_f32_e32 v89, v111, v89
	v_add_f32_e32 v71, 1.0, v71
	v_rcp_f32_e32 v71, v71
	v_mov_b32_dpp v13, v21 row_shr:2 row_mask:0xf bank_mask:0xf
	v_fmac_f32_e32 v89, v21, v103
	v_fmac_f32_e32 v89, v99, v13
	v_add_f32_e32 v13, v109, v89
	v_mul_f32_e32 v12, v12, v71
	v_mul_f32_e32 v12, v13, v12
	v_cvt_pk_bf16_f32 v12, v9, v12
	v_mov_b32_dpp v9, v118 row_ror:1 row_mask:0xf bank_mask:0xf bound_ctrl:1
	v_mov_b32_dpp v13, v118 row_ror:2 row_mask:0xf bank_mask:0xf bound_ctrl:1
	v_mov_b32_dpp v71, v20 row_ror:1 row_mask:0xf bank_mask:0xf bound_ctrl:1
	v_mov_b32_dpp v9, v4 row_shr:1 row_mask:0xf bank_mask:0xf
	v_mul_f32_e32 v9, v116, v9
	v_mov_b32_dpp v13, v4 row_shr:2 row_mask:0xf bank_mask:0xf
	v_fmac_f32_e32 v9, v4, v114
	v_fmac_f32_e32 v9, v100, v13
	v_add_f32_e32 v9, v112, v9
	v_mul_f32_e32 v13, 0xbfb8aa3b, v9
	v_exp_f32_e32 v13, v13
	v_mov_b32_dpp v71, v0 row_shr:1 row_mask:0xf bank_mask:0xf
	v_mov_b32_dpp v20, v20 row_ror:2 row_mask:0xf bank_mask:0xf bound_ctrl:1
	v_mul_f32_e32 v71, v110, v71
	v_add_f32_e32 v13, 1.0, v13
	v_rcp_f32_e32 v13, v13
	v_mov_b32_dpp v20, v0 row_shr:2 row_mask:0xf bank_mask:0xf
	v_fmac_f32_e32 v71, v0, v102
	v_fmac_f32_e32 v71, v98, v20
	v_mul_f32_e32 v9, v9, v13
	v_mov_b32_dpp v13, v119 row_ror:1 row_mask:0xf bank_mask:0xf bound_ctrl:1
	v_add_f32_e32 v20, v108, v71
	v_mul_f32_e32 v9, v20, v9
	v_mov_b32_dpp v13, v5 row_shr:1 row_mask:0xf bank_mask:0xf
	v_mov_b32_dpp v20, v119 row_ror:2 row_mask:0xf bank_mask:0xf bound_ctrl:1
	v_mul_f32_e32 v13, v117, v13
	v_fmac_f32_e32 v13, v5, v115
	v_mov_b32_dpp v20, v5 row_shr:2 row_mask:0xf bank_mask:0xf
	v_fmac_f32_e32 v13, v101, v20
	v_add_f32_e32 v13, v113, v13
	v_mul_f32_e32 v20, 0xbfb8aa3b, v13
	v_exp_f32_e32 v20, v20
	v_mov_b32_dpp v71, v21 row_ror:1 row_mask:0xf bank_mask:0xf bound_ctrl:1
	v_mov_b32_dpp v21, v21 row_ror:2 row_mask:0xf bank_mask:0xf bound_ctrl:1
	v_add_f32_e32 v20, 1.0, v20
	v_mov_b32_dpp v71, v1 row_shr:1 row_mask:0xf bank_mask:0xf
	v_rcp_f32_e32 v20, v20
	v_mul_f32_e32 v71, v111, v71
	v_mov_b32_dpp v21, v1 row_shr:2 row_mask:0xf bank_mask:0xf
	v_fmac_f32_e32 v71, v1, v103
	v_fmac_f32_e32 v71, v99, v21
	v_add_f32_e32 v21, v109, v71
	v_mul_f32_e32 v13, v13, v20
	v_mul_f32_e32 v13, v21, v13
	v_cvt_pk_bf16_f32 v20, v9, v13
	s_waitcnt vmcnt(5)
	s_nop 0
	v_mul_f32_dpp v13, v62, v68 row_shr:1 row_mask:0xf bank_mask:0xf bound_ctrl:1
	v_mov_b32_dpp v9, v62 row_shr:2 row_mask:0xf bank_mask:0xf bound_ctrl:1
	s_waitcnt vmcnt(4)
	v_fmac_f32_e32 v13, v62, v66
	v_fmac_f32_e32 v13, v40, v9
	v_add_f32_e32 v9, v64, v13
	v_mul_f32_e32 v13, 0xbfb8aa3b, v9
	v_exp_f32_e32 v13, v13
	s_waitcnt vmcnt(2)
	v_mul_f32_dpp v71, v58, v52 row_shr:1 row_mask:0xf bank_mask:0xf bound_ctrl:1
	v_mov_b32_dpp v21, v58 row_shr:2 row_mask:0xf bank_mask:0xf bound_ctrl:1
	s_waitcnt vmcnt(1)
	v_fmac_f32_e32 v71, v58, v44
	v_add_f32_e32 v13, 1.0, v13
	v_rcp_f32_e32 v13, v13
	v_fmac_f32_e32 v71, v16, v21
	s_waitcnt vmcnt(0)
	v_add_f32_e32 v21, v48, v71
	v_mul_f32_dpp v89, v59, v53 row_shr:1 row_mask:0xf bank_mask:0xf bound_ctrl:1
	v_mul_f32_dpp v71, v63, v69 row_shr:1 row_mask:0xf bank_mask:0xf bound_ctrl:1
	v_mul_f32_e32 v9, v9, v13
	v_mov_b32_dpp v13, v63 row_shr:2 row_mask:0xf bank_mask:0xf bound_ctrl:1
	v_fmac_f32_e32 v71, v63, v67
	v_fmac_f32_e32 v71, v41, v13
	v_add_f32_e32 v13, v65, v71
	v_mul_f32_e32 v71, 0xbfb8aa3b, v13
	v_exp_f32_e32 v71, v71
	v_mul_f32_e32 v9, v21, v9
	v_mov_b32_dpp v21, v59 row_shr:2 row_mask:0xf bank_mask:0xf bound_ctrl:1
	v_fmac_f32_e32 v89, v59, v45
	v_add_f32_e32 v71, 1.0, v71
	v_rcp_f32_e32 v71, v71
	v_fmac_f32_e32 v89, v17, v21
	v_add_f32_e32 v21, v49, v89
	v_mul_f32_e32 v13, v13, v71
	v_mul_f32_e32 v13, v21, v13
	v_cvt_pk_bf16_f32 v95, v9, v13
	s_and_saveexec_b64 s[62:63], s[2:3]
	s_xor_b64 s[62:63], exec, s[62:63]
	s_cbranch_execz .LBB0_507
	v_mov_b64_e32 v[80:81], s[48:49]
	v_mad_i64_i32 v[80:81], s[64:65], v156, s93, v[80:81]
	v_lshl_add_u64 v[80:81], v[146:147], 1, v[80:81]
	v_mov_b32_e32 v232, v251
	v_mov_b32_e32 v233, v252
	v_mov_b32_e32 v234, v94
	v_mov_b32_e32 v235, v95
	s_nop 1
	v_permlane16_swap_b32_e32 v232, v234
	v_permlane16_swap_b32_e32 v233, v235
	v_lshl_add_u64 v[236:237], v[80:81], 0, v[238:239]
	global_store_dwordx4 v[236:237], v[232:235], off
	s_nop 1

.LBB0_512:
	s_or_b64 exec, exec, s[62:63]
	v_mov_b32_e32 v155, v154
	v_pk_mul_f32 v[30:31], v[30:31], v[154:155]
	v_pk_mul_f32 v[26:27], v[26:27], v[154:155]
	s_nop 0
	v_mul_f32_dpp v13, v30, v68 row_shr:1 row_mask:0xf bank_mask:0xf bound_ctrl:1
	v_mov_b32_dpp v9, v30 row_shr:2 row_mask:0xf bank_mask:0xf bound_ctrl:1
	v_fmac_f32_e32 v13, v30, v66
	v_fmac_f32_e32 v13, v40, v9
	v_add_f32_e32 v9, v64, v13
	v_mul_f32_e32 v13, 0xbfb8aa3b, v9
	v_exp_f32_e32 v13, v13
	v_mul_f32_dpp v32, v26, v52 row_shr:1 row_mask:0xf bank_mask:0xf bound_ctrl:1
	v_mov_b32_dpp v21, v26 row_shr:2 row_mask:0xf bank_mask:0xf bound_ctrl:1
	v_fmac_f32_e32 v32, v26, v44
	v_add_f32_e32 v13, 1.0, v13
	v_rcp_f32_e32 v13, v13
	v_fmac_f32_e32 v32, v16, v21
	v_mul_f32_dpp v21, v31, v69 row_shr:1 row_mask:0xf bank_mask:0xf bound_ctrl:1
	v_fmac_f32_e32 v21, v31, v67
	v_mul_f32_e32 v9, v9, v13
	v_mov_b32_dpp v13, v31 row_shr:2 row_mask:0xf bank_mask:0xf bound_ctrl:1
	v_fmac_f32_e32 v21, v41, v13
	v_add_f32_e32 v13, v65, v21
	v_mul_f32_e32 v21, 0xbfb8aa3b, v13
	v_exp_f32_e32 v21, v21
	v_add_f32_e32 v16, v48, v32
	v_mul_f32_dpp v32, v27, v53 row_shr:1 row_mask:0xf bank_mask:0xf bound_ctrl:1
	v_mul_f32_e32 v9, v16, v9
	v_add_f32_e32 v21, 1.0, v21
	v_rcp_f32_e32 v21, v21
	v_mov_b32_dpp v16, v27 row_shr:2 row_mask:0xf bank_mask:0xf bound_ctrl:1
	v_fmac_f32_e32 v32, v27, v45
	v_fmac_f32_e32 v32, v17, v16
	v_add_f32_e32 v16, v49, v32
	v_mul_f32_e32 v13, v13, v21
	v_mul_f32_e32 v13, v16, v13
	v_cvt_pk_bf16_f32 v71, v9, v13
	s_and_saveexec_b64 s[62:63], s[2:3]
	s_xor_b64 s[62:63], exec, s[62:63]
	s_cbranch_execz .LBB0_514
	v_mov_b64_e32 v[16:17], s[48:49]
	v_mad_i64_i32 v[16:17], s[64:65], v157, s93, v[16:17]
	v_lshl_add_u64 v[16:17], v[146:147], 1, v[16:17]
	v_mov_b32_e32 v232, v253
	v_mov_b32_e32 v233, v254
	v_mov_b32_e32 v234, v70
	v_mov_b32_e32 v235, v71
	s_nop 1
	v_permlane16_swap_b32_e32 v232, v234
	v_permlane16_swap_b32_e32 v233, v235
	v_lshl_add_u64 v[236:237], v[16:17], 0, v[238:239]
	global_store_dwordx4 v[236:237], v[232:235], off
	s_nop 1

.LBB0_1212:
	s_lshl_b32 s51, s58, 8
	s_add_i32 s51, s51, s78
	v_or_b32_e32 v156, s51, v210
	v_ashrrev_i32_e32 v157, 31, v156
	v_or_b32_e32 v170, 16, v156
	v_or_b32_e32 v168, 32, v156
	v_or_b32_e32 v166, 48, v156
	v_lshlrev_b64 v[146:147], 6, v[156:157]
	v_ashrrev_i32_e32 v171, 31, v170
	v_ashrrev_i32_e32 v169, 31, v168
	v_ashrrev_i32_e32 v167, 31, v166
	v_lshl_add_u64 v[154:155], v[136:137], 0, v[146:147]
	v_lshlrev_b64 v[146:147], 6, v[170:171]
	v_lshlrev_b64 v[158:159], 6, v[168:169]
	v_lshlrev_b64 v[162:163], 6, v[166:167]
	v_lshl_add_u64 v[150:151], v[136:137], 0, v[146:147]
	v_lshl_add_u64 v[158:159], v[136:137], 0, v[158:159]
	v_lshl_add_u64 v[162:163], v[136:137], 0, v[162:163]
	global_load_dwordx4 v[146:149], v[154:155], off
	s_nop 0
	global_load_dwordx4 v[150:153], v[150:151], off
	s_waitcnt vmcnt(0)
	v_mov_b32_e32 v172, v147
	global_load_dwordx4 v[158:161], v[158:159], off
	v_mov_b32_e32 v173, v148
	global_load_dwordx4 v[162:165], v[162:163], off
	v_mov_b32_e32 v147, v149
	v_pk_add_f32 v[146:147], v[172:173], v[146:147]
	v_mov_b32_e32 v148, v151
	v_mov_b32_e32 v149, v152
	v_mov_b32_e32 v151, v153
	v_add_f32_e32 v157, v146, v147
	v_pk_add_f32 v[146:147], v[148:149], v[150:151]
	s_waitcnt vmcnt(1)
	v_mov_b32_e32 v152, v159
	v_mov_b32_e32 v153, v160
	v_mov_b32_e32 v159, v161
	s_waitcnt vmcnt(0)
	v_mov_b32_e32 v160, v163
	v_mov_b32_e32 v161, v164
	v_mov_b32_e32 v163, v165
	v_pk_add_f32 v[148:149], v[152:153], v[158:159]
	v_pk_add_f32 v[150:151], v[160:161], v[162:163]
	v_add_f32_e32 v146, v146, v147
	v_add_f32_e32 v147, v148, v149
	v_add_f32_e32 v148, v150, v151
	ds_bpermute_b32 v152, v212, v157
	ds_bpermute_b32 v149, v212, v146
	ds_bpermute_b32 v150, v212, v147
	ds_bpermute_b32 v151, v212, v148
	s_waitcnt lgkmcnt(3)
	v_add_f32_e32 v152, v157, v152
	s_waitcnt lgkmcnt(2)
	v_add_f32_e32 v146, v146, v149
	s_waitcnt lgkmcnt(1)
	v_add_f32_e32 v147, v147, v150
	s_waitcnt lgkmcnt(0)
	v_add_f32_e32 v148, v148, v151
	ds_bpermute_b32 v153, v213, v152
	ds_bpermute_b32 v149, v213, v146
	ds_bpermute_b32 v150, v213, v147
	ds_bpermute_b32 v151, v213, v148
	s_waitcnt lgkmcnt(3)
	v_add_f32_e32 v152, v152, v153
	s_waitcnt lgkmcnt(2)
	v_add_f32_e32 v146, v146, v149
	s_waitcnt lgkmcnt(1)
	v_add_f32_e32 v147, v147, v150
	s_waitcnt lgkmcnt(0)
	v_add_f32_e32 v148, v148, v151
	v_fmamk_f32 v152, v152, 0x3a800000, v219
	v_fmamk_f32 v146, v146, 0x3a800000, v219
	v_fmamk_f32 v147, v147, 0x3a800000, v219
	v_fmamk_f32 v148, v148, 0x3a800000, v219
	v_rsq_f32_e32 v164, v152
	v_rsq_f32_e32 v162, v146
	v_rsq_f32_e32 v160, v147
	v_rsq_f32_e32 v158, v148
	v_add_co_u32_e32 v154, vcc, s73, v154
	s_nop 1
	v_addc_co_u32_e32 v155, vcc, 0, v155, vcc
	global_load_dwordx4 v[146:149], v[154:155], off
	global_load_dwordx4 v[150:153], v[154:155], off offset:1024
	global_load_dwordx4 v[172:175], v[154:155], off offset:2048
	global_load_dwordx4 v[176:179], v[154:155], off offset:3072
	s_waitcnt vmcnt(3)
	v_mov_b32_e32 v154, v147
	v_mov_b32_e32 v155, v148
	v_mov_b32_e32 v147, v149
	s_waitcnt vmcnt(2)
	v_mov_b32_e32 v148, v151
	v_mov_b32_e32 v149, v152
	v_mov_b32_e32 v151, v153
	s_waitcnt vmcnt(1)
	v_mov_b32_e32 v152, v173
	v_mov_b32_e32 v153, v174
	v_mov_b32_e32 v173, v175
	s_waitcnt vmcnt(0)
	v_mov_b32_e32 v174, v177
	v_mov_b32_e32 v175, v178
	v_mov_b32_e32 v177, v179
	v_pk_add_f32 v[146:147], v[154:155], v[146:147]
	v_pk_add_f32 v[148:149], v[148:149], v[150:151]
	v_pk_add_f32 v[150:151], v[152:153], v[172:173]
	v_pk_add_f32 v[152:153], v[174:175], v[176:177]
	v_add_f32_e32 v146, v146, v147
	v_add_f32_e32 v147, v148, v149
	v_add_f32_e32 v148, v150, v151
	v_add_f32_e32 v149, v152, v153
	ds_bpermute_b32 v150, v212, v146
	ds_bpermute_b32 v151, v212, v147
	ds_bpermute_b32 v152, v212, v148
	ds_bpermute_b32 v153, v212, v149
	s_waitcnt lgkmcnt(3)
	v_add_f32_e32 v146, v146, v150
	s_waitcnt lgkmcnt(2)
	v_add_f32_e32 v147, v147, v151
	s_waitcnt lgkmcnt(1)
	v_add_f32_e32 v148, v148, v152
	s_waitcnt lgkmcnt(0)
	v_add_f32_e32 v149, v149, v153
	ds_bpermute_b32 v150, v213, v146
	ds_bpermute_b32 v151, v213, v147
	ds_bpermute_b32 v152, v213, v148
	ds_bpermute_b32 v153, v213, v149
	s_waitcnt lgkmcnt(3)
	v_add_f32_e32 v146, v146, v150
	s_waitcnt lgkmcnt(2)
	v_add_f32_e32 v147, v147, v151
	s_waitcnt lgkmcnt(1)
	v_add_f32_e32 v148, v148, v152
	s_waitcnt lgkmcnt(0)
	v_add_f32_e32 v149, v149, v153
	v_fmamk_f32 v146, v146, 0x3a800000, v219
	v_fmamk_f32 v147, v147, 0x3a800000, v219
	v_fmamk_f32 v148, v148, 0x3a800000, v219
	v_fmamk_f32 v149, v149, 0x3a800000, v219
	v_rsq_f32_e32 v154, v146
	v_rsq_f32_e32 v152, v147
	v_rsq_f32_e32 v150, v148
	v_rsq_f32_e32 v148, v149
	v_lshl_or_b32 v146, s56, 7, v215
	v_ashrrev_i32_e32 v147, 31, v146
	v_lshlrev_b64 v[172:173], 2, v[146:147]
	v_lshl_add_u64 v[174:175], s[16:17], 0, v[172:173]
	v_lshl_add_u64 v[176:177], s[8:9], 0, v[172:173]
	v_lshl_add_u64 v[178:179], s[24:25], 0, v[172:173]
	global_load_dwordx2 v[202:203], v[174:175], off
	global_load_dwordx2 v[208:209], v[176:177], off
	global_load_dwordx2 v[206:207], v[178:179], off
	v_lshl_add_u64 v[174:175], s[18:19], 0, v[172:173]
	global_load_dwordx2 v[204:205], v[174:175], off
	v_lshl_add_u64 v[174:175], s[26:27], 0, v[172:173]
	v_lshl_add_u64 v[178:179], s[28:29], 0, v[172:173]
	v_lshl_add_u64 v[180:181], s[30:31], 0, v[172:173]
	global_load_dwordx2 v[176:177], v[174:175], off
	global_load_dwordx2 v[200:201], v[178:179], off
	global_load_dwordx2 v[196:197], v[180:181], off
	v_lshl_add_u64 v[172:173], s[42:43], 0, v[172:173]
	global_load_dwordx2 v[198:199], v[172:173], off
	v_pk_mul_f32 v[126:127], v[126:127], v[164:165] op_sel_hi:[1,0]
	v_pk_mul_f32 v[124:125], v[124:125], v[164:165] op_sel_hi:[1,0]
	v_pk_mul_f32 v[122:123], v[122:123], v[164:165] op_sel_hi:[1,0]
	v_pk_mul_f32 v[120:121], v[120:121], v[164:165] op_sel_hi:[1,0]
	v_pk_mul_f32 v[180:181], v[116:117], v[162:163] op_sel_hi:[1,0]
	v_pk_mul_f32 v[182:183], v[104:105], v[162:163] op_sel_hi:[1,0]
	v_pk_mul_f32 v[178:179], v[112:113], v[160:161] op_sel_hi:[1,0]
	v_pk_mul_f32 v[172:173], v[100:101], v[160:161] op_sel_hi:[1,0]
	v_pk_mul_f32 v[100:101], v[108:109], v[158:159] op_sel_hi:[1,0]
	v_pk_mul_f32 v[96:97], v[96:97], v[158:159] op_sel_hi:[1,0]
	v_pk_mul_f32 v[92:93], v[92:93], v[154:155] op_sel_hi:[1,0]
	v_pk_mul_f32 v[88:89], v[88:89], v[154:155] op_sel_hi:[1,0]
	v_pk_mul_f32 v[116:117], v[84:85], v[152:153] op_sel_hi:[1,0]
	v_pk_mul_f32 v[84:85], v[68:69], v[150:151] op_sel_hi:[1,0]
	v_pk_mul_f32 v[68:69], v[76:77], v[148:149] op_sel_hi:[1,0]
	v_pk_mul_f32 v[64:65], v[64:65], v[148:149] op_sel_hi:[1,0]
	v_pk_mul_f32 v[112:113], v[72:73], v[152:153] op_sel_hi:[1,0]
	v_pk_mul_f32 v[104:105], v[80:81], v[150:151] op_sel_hi:[1,0]
	s_waitcnt vmcnt(6)
	v_mul_f32_dpp v73, v124, v208 row_shr:1 row_mask:0xf bank_mask:0xf bound_ctrl:1
	v_mov_b32_dpp v72, v124 row_shr:2 row_mask:0xf bank_mask:0xf bound_ctrl:1
	s_waitcnt vmcnt(5)
	v_fmac_f32_e32 v73, v124, v206
	v_fmac_f32_e32 v73, v202, v72
	s_waitcnt vmcnt(4)
	v_add_f32_e32 v72, v204, v73
	v_mul_f32_e32 v73, 0xbfb8aa3b, v72
	v_exp_f32_e32 v73, v73
	s_waitcnt vmcnt(2)
	v_mul_f32_dpp v77, v120, v200 row_shr:1 row_mask:0xf bank_mask:0xf bound_ctrl:1
	v_mov_b32_dpp v76, v120 row_shr:2 row_mask:0xf bank_mask:0xf bound_ctrl:1
	s_waitcnt vmcnt(1)
	v_fmac_f32_e32 v77, v120, v196
	v_add_f32_e32 v73, 1.0, v73
	v_rcp_f32_e32 v73, v73
	v_fmac_f32_e32 v77, v176, v76
	s_waitcnt vmcnt(0)
	v_add_f32_e32 v76, v198, v77
	v_mul_f32_dpp v80, v121, v201 row_shr:1 row_mask:0xf bank_mask:0xf bound_ctrl:1
	v_mul_f32_dpp v77, v125, v209 row_shr:1 row_mask:0xf bank_mask:0xf bound_ctrl:1
	v_mul_f32_e32 v72, v72, v73
	v_mov_b32_dpp v73, v125 row_shr:2 row_mask:0xf bank_mask:0xf bound_ctrl:1
	v_fmac_f32_e32 v77, v125, v207
	v_fmac_f32_e32 v77, v203, v73
	v_add_f32_e32 v73, v205, v77
	v_mul_f32_e32 v77, 0xbfb8aa3b, v73
	v_exp_f32_e32 v77, v77
	v_mul_f32_e32 v72, v76, v72
	v_mov_b32_dpp v76, v121 row_shr:2 row_mask:0xf bank_mask:0xf bound_ctrl:1
	v_fmac_f32_e32 v80, v121, v197
	v_add_f32_e32 v77, 1.0, v77
	v_rcp_f32_e32 v77, v77
	v_fmac_f32_e32 v80, v177, v76
	v_add_f32_e32 v76, v199, v80
	v_or_b32_e32 v174, 2, v146
	v_mul_f32_e32 v73, v73, v77
	v_mul_f32_e32 v73, v76, v73
	v_cvt_pk_bf16_f32 v80, v72, v73
	v_ashrrev_i32_e32 v175, 31, v174
	v_mov_b32_dpp v72, v124 row_ror:1 row_mask:0xf bank_mask:0xf bound_ctrl:1
	v_mov_b32_dpp v73, v124 row_ror:2 row_mask:0xf bank_mask:0xf bound_ctrl:1
	v_mov_b32_dpp v76, v120 row_ror:1 row_mask:0xf bank_mask:0xf bound_ctrl:1
	v_mov_b32_dpp v72, v180 row_shr:1 row_mask:0xf bank_mask:0xf
	v_mul_f32_e32 v72, v208, v72
	v_mov_b32_dpp v73, v180 row_shr:2 row_mask:0xf bank_mask:0xf
	v_fmac_f32_e32 v72, v180, v206
	v_fmac_f32_e32 v72, v202, v73
	v_add_f32_e32 v72, v204, v72
	v_mul_f32_e32 v73, 0xbfb8aa3b, v72
	v_exp_f32_e32 v73, v73
	v_mov_b32_dpp v76, v182 row_shr:1 row_mask:0xf bank_mask:0xf
	v_mov_b32_dpp v77, v120 row_ror:2 row_mask:0xf bank_mask:0xf bound_ctrl:1
	v_mul_f32_e32 v76, v200, v76
	v_add_f32_e32 v73, 1.0, v73
	v_rcp_f32_e32 v73, v73
	v_mov_b32_dpp v77, v182 row_shr:2 row_mask:0xf bank_mask:0xf
	v_fmac_f32_e32 v76, v182, v196
	v_fmac_f32_e32 v76, v176, v77
	v_mul_f32_e32 v72, v72, v73
	v_mov_b32_dpp v73, v125 row_ror:1 row_mask:0xf bank_mask:0xf bound_ctrl:1
	v_add_f32_e32 v76, v198, v76
	v_mul_f32_e32 v72, v76, v72
	v_mov_b32_dpp v73, v181 row_shr:1 row_mask:0xf bank_mask:0xf
	v_mov_b32_dpp v76, v125 row_ror:2 row_mask:0xf bank_mask:0xf bound_ctrl:1
	v_mul_f32_e32 v73, v209, v73
	v_fmac_f32_e32 v73, v181, v207
	v_mov_b32_dpp v76, v181 row_shr:2 row_mask:0xf bank_mask:0xf
	v_fmac_f32_e32 v73, v203, v76
	v_add_f32_e32 v73, v205, v73
	v_mul_f32_e32 v76, 0xbfb8aa3b, v73
	v_exp_f32_e32 v76, v76
	v_mov_b32_dpp v77, v121 row_ror:1 row_mask:0xf bank_mask:0xf bound_ctrl:1
	v_mov_b32_dpp v81, v121 row_ror:2 row_mask:0xf bank_mask:0xf bound_ctrl:1
	v_add_f32_e32 v76, 1.0, v76
	v_mov_b32_dpp v77, v183 row_shr:1 row_mask:0xf bank_mask:0xf
	v_rcp_f32_e32 v76, v76
	v_mul_f32_e32 v77, v201, v77
	v_mov_b32_dpp v81, v183 row_shr:2 row_mask:0xf bank_mask:0xf
	v_fmac_f32_e32 v77, v183, v197
	v_fmac_f32_e32 v77, v177, v81
	v_add_f32_e32 v77, v199, v77
	v_mul_f32_e32 v73, v73, v76
	v_mul_f32_e32 v73, v77, v73
	v_cvt_pk_bf16_f32 v72, v72, v73
	s_nop 1
	v_mov_b32_dpp v73, v180 row_ror:1 row_mask:0xf bank_mask:0xf bound_ctrl:1
	v_mov_b32_dpp v76, v180 row_ror:2 row_mask:0xf bank_mask:0xf bound_ctrl:1
	v_mov_b32_dpp v77, v182 row_ror:1 row_mask:0xf bank_mask:0xf bound_ctrl:1
	v_mov_b32_dpp v73, v178 row_shr:1 row_mask:0xf bank_mask:0xf
	v_mul_f32_e32 v73, v208, v73
	v_mov_b32_dpp v76, v178 row_shr:2 row_mask:0xf bank_mask:0xf
	v_fmac_f32_e32 v73, v178, v206
	v_fmac_f32_e32 v73, v202, v76
	v_add_f32_e32 v73, v204, v73
	v_mul_f32_e32 v76, 0xbfb8aa3b, v73
	v_exp_f32_e32 v76, v76
	v_mov_b32_dpp v77, v172 row_shr:1 row_mask:0xf bank_mask:0xf
	v_mov_b32_dpp v81, v182 row_ror:2 row_mask:0xf bank_mask:0xf bound_ctrl:1
	v_mul_f32_e32 v77, v200, v77
	v_add_f32_e32 v76, 1.0, v76
	v_rcp_f32_e32 v76, v76
	v_mov_b32_dpp v81, v172 row_shr:2 row_mask:0xf bank_mask:0xf
	v_fmac_f32_e32 v77, v172, v196
	v_fmac_f32_e32 v77, v176, v81
	v_mul_f32_e32 v73, v73, v76
	v_mov_b32_dpp v76, v181 row_ror:1 row_mask:0xf bank_mask:0xf bound_ctrl:1
	v_add_f32_e32 v77, v198, v77
	v_mul_f32_e32 v73, v77, v73
	v_mov_b32_dpp v76, v179 row_shr:1 row_mask:0xf bank_mask:0xf
	v_mov_b32_dpp v77, v181 row_ror:2 row_mask:0xf bank_mask:0xf bound_ctrl:1
	v_mul_f32_e32 v76, v209, v76
	v_fmac_f32_e32 v76, v179, v207
	v_mov_b32_dpp v77, v179 row_shr:2 row_mask:0xf bank_mask:0xf
	v_fmac_f32_e32 v76, v203, v77
	v_add_f32_e32 v76, v205, v76
	v_mul_f32_e32 v77, 0xbfb8aa3b, v76
	v_exp_f32_e32 v77, v77
	v_mov_b32_dpp v81, v183 row_ror:1 row_mask:0xf bank_mask:0xf bound_ctrl:1
	v_mov_b32_dpp v108, v183 row_ror:2 row_mask:0xf bank_mask:0xf bound_ctrl:1
	v_add_f32_e32 v77, 1.0, v77
	v_mov_b32_dpp v81, v173 row_shr:1 row_mask:0xf bank_mask:0xf
	v_rcp_f32_e32 v77, v77
	v_mul_f32_e32 v81, v201, v81
	v_mov_b32_dpp v108, v173 row_shr:2 row_mask:0xf bank_mask:0xf
	v_fmac_f32_e32 v81, v173, v197
	v_fmac_f32_e32 v81, v177, v108
	v_add_f32_e32 v81, v199, v81
	v_mul_f32_e32 v76, v76, v77
	v_mul_f32_e32 v76, v81, v76
	v_cvt_pk_bf16_f32 v76, v73, v76
	v_mov_b32_dpp v73, v178 row_ror:1 row_mask:0xf bank_mask:0xf bound_ctrl:1
	v_mov_b32_dpp v77, v178 row_ror:2 row_mask:0xf bank_mask:0xf bound_ctrl:1
	v_mov_b32_dpp v81, v172 row_ror:1 row_mask:0xf bank_mask:0xf bound_ctrl:1
	v_mov_b32_dpp v73, v100 row_shr:1 row_mask:0xf bank_mask:0xf
	v_mul_f32_e32 v73, v208, v73
	v_mov_b32_dpp v77, v100 row_shr:2 row_mask:0xf bank_mask:0xf
	v_fmac_f32_e32 v73, v100, v206
	v_fmac_f32_e32 v73, v202, v77
	v_add_f32_e32 v73, v204, v73
	v_mul_f32_e32 v77, 0xbfb8aa3b, v73
	v_exp_f32_e32 v77, v77
	v_mov_b32_dpp v81, v96 row_shr:1 row_mask:0xf bank_mask:0xf
	v_mov_b32_dpp v108, v172 row_ror:2 row_mask:0xf bank_mask:0xf bound_ctrl:1
	v_mul_f32_e32 v81, v200, v81
	v_add_f32_e32 v77, 1.0, v77
	v_rcp_f32_e32 v77, v77
	v_mov_b32_dpp v108, v96 row_shr:2 row_mask:0xf bank_mask:0xf
	v_fmac_f32_e32 v81, v96, v196
	v_fmac_f32_e32 v81, v176, v108
	v_mul_f32_e32 v73, v73, v77
	v_mov_b32_dpp v77, v179 row_ror:1 row_mask:0xf bank_mask:0xf bound_ctrl:1
	v_add_f32_e32 v81, v198, v81
	v_mul_f32_e32 v73, v81, v73
	v_mov_b32_dpp v77, v101 row_shr:1 row_mask:0xf bank_mask:0xf
	v_mov_b32_dpp v81, v179 row_ror:2 row_mask:0xf bank_mask:0xf bound_ctrl:1
	v_mul_f32_e32 v77, v209, v77
	v_fmac_f32_e32 v77, v101, v207
	v_mov_b32_dpp v81, v101 row_shr:2 row_mask:0xf bank_mask:0xf
	v_fmac_f32_e32 v77, v203, v81
	v_add_f32_e32 v77, v205, v77
	v_mul_f32_e32 v81, 0xbfb8aa3b, v77
	v_exp_f32_e32 v81, v81
	v_mov_b32_dpp v108, v173 row_ror:1 row_mask:0xf bank_mask:0xf bound_ctrl:1
	v_mov_b32_dpp v109, v173 row_ror:2 row_mask:0xf bank_mask:0xf bound_ctrl:1
	v_add_f32_e32 v81, 1.0, v81
	v_mov_b32_dpp v108, v97 row_shr:1 row_mask:0xf bank_mask:0xf
	v_rcp_f32_e32 v81, v81
	v_mul_f32_e32 v108, v201, v108
	v_mov_b32_dpp v109, v97 row_shr:2 row_mask:0xf bank_mask:0xf
	v_fmac_f32_e32 v108, v97, v197
	v_fmac_f32_e32 v108, v177, v109
	v_add_f32_e32 v108, v199, v108
	v_mul_f32_e32 v77, v77, v81
	v_mul_f32_e32 v77, v108, v77
	v_cvt_pk_bf16_f32 v108, v73, v77
	v_lshlrev_b64 v[172:173], 2, v[174:175]
	v_lshl_add_u64 v[174:175], s[16:17], 0, v[172:173]
	v_lshl_add_u64 v[178:179], s[8:9], 0, v[172:173]
	v_lshl_add_u64 v[180:181], s[24:25], 0, v[172:173]
	global_load_dwordx2 v[186:187], v[174:175], off
	global_load_dwordx2 v[192:193], v[178:179], off
	global_load_dwordx2 v[190:191], v[180:181], off
	v_lshl_add_u64 v[174:175], s[18:19], 0, v[172:173]
	global_load_dwordx2 v[188:189], v[174:175], off
	v_lshl_add_u64 v[174:175], s[26:27], 0, v[172:173]
	v_lshl_add_u64 v[180:181], s[28:29], 0, v[172:173]
	v_lshl_add_u64 v[182:183], s[30:31], 0, v[172:173]
	global_load_dwordx2 v[178:179], v[174:175], off
	global_load_dwordx2 v[184:185], v[180:181], off
	s_nop 0
	global_load_dwordx2 v[180:181], v[182:183], off
	v_lshl_add_u64 v[172:173], s[42:43], 0, v[172:173]
	global_load_dwordx2 v[182:183], v[172:173], off
	v_mul_f32_dpp v77, v92, v208 row_shr:1 row_mask:0xf bank_mask:0xf bound_ctrl:1
	v_mov_b32_dpp v73, v92 row_shr:2 row_mask:0xf bank_mask:0xf bound_ctrl:1
	v_fmac_f32_e32 v77, v92, v206
	v_fmac_f32_e32 v77, v202, v73
	v_add_f32_e32 v73, v204, v77
	v_mul_f32_e32 v77, 0xbfb8aa3b, v73
	v_exp_f32_e32 v77, v77
	v_mul_f32_dpp v109, v88, v200 row_shr:1 row_mask:0xf bank_mask:0xf bound_ctrl:1
	v_mov_b32_dpp v81, v88 row_shr:2 row_mask:0xf bank_mask:0xf bound_ctrl:1
	v_fmac_f32_e32 v109, v88, v196
	v_add_f32_e32 v77, 1.0, v77
	v_rcp_f32_e32 v77, v77
	v_fmac_f32_e32 v109, v176, v81
	v_add_f32_e32 v81, v198, v109
	v_mul_f32_dpp v149, v89, v201 row_shr:1 row_mask:0xf bank_mask:0xf bound_ctrl:1
	v_mul_f32_dpp v109, v93, v209 row_shr:1 row_mask:0xf bank_mask:0xf bound_ctrl:1
	v_mul_f32_e32 v73, v73, v77
	v_mov_b32_dpp v77, v93 row_shr:2 row_mask:0xf bank_mask:0xf bound_ctrl:1
	v_fmac_f32_e32 v109, v93, v207
	v_fmac_f32_e32 v109, v203, v77
	v_add_f32_e32 v77, v205, v109
	v_mul_f32_e32 v109, 0xbfb8aa3b, v77
	v_exp_f32_e32 v109, v109
	v_mul_f32_e32 v73, v81, v73
	v_mov_b32_dpp v81, v89 row_shr:2 row_mask:0xf bank_mask:0xf bound_ctrl:1
	v_fmac_f32_e32 v149, v89, v197
	v_add_f32_e32 v109, 1.0, v109
	v_rcp_f32_e32 v109, v109
	v_fmac_f32_e32 v149, v177, v81
	v_add_f32_e32 v81, v199, v149
	v_mul_f32_e32 v77, v77, v109
	v_mul_f32_e32 v77, v81, v77
	v_cvt_pk_bf16_f32 v194, v73, v77
	v_mov_b32_dpp v73, v92 row_ror:1 row_mask:0xf bank_mask:0xf bound_ctrl:1
	s_nop 0
	v_mov_b32_dpp v77, v92 row_ror:2 row_mask:0xf bank_mask:0xf bound_ctrl:1
	v_mov_b32_dpp v81, v88 row_ror:1 row_mask:0xf bank_mask:0xf bound_ctrl:1
	v_mov_b32_dpp v73, v116 row_shr:1 row_mask:0xf bank_mask:0xf
	v_mul_f32_e32 v73, v208, v73
	v_mov_b32_dpp v77, v116 row_shr:2 row_mask:0xf bank_mask:0xf
	v_fmac_f32_e32 v73, v206, v116
	v_fmac_f32_e32 v73, v202, v77
	v_add_f32_e32 v73, v204, v73
	v_mul_f32_e32 v77, 0xbfb8aa3b, v73
	v_exp_f32_e32 v77, v77
	v_mov_b32_dpp v81, v112 row_shr:1 row_mask:0xf bank_mask:0xf
	v_mov_b32_dpp v109, v88 row_ror:2 row_mask:0xf bank_mask:0xf bound_ctrl:1
	v_mul_f32_e32 v81, v200, v81
	v_add_f32_e32 v77, 1.0, v77
	v_rcp_f32_e32 v77, v77
	v_mov_b32_dpp v109, v112 row_shr:2 row_mask:0xf bank_mask:0xf
	v_fmac_f32_e32 v81, v112, v196
	v_fmac_f32_e32 v81, v176, v109
	v_mul_f32_e32 v73, v73, v77
	v_mov_b32_dpp v77, v93 row_ror:1 row_mask:0xf bank_mask:0xf bound_ctrl:1
	v_add_f32_e32 v81, v198, v81
	v_mul_f32_e32 v73, v81, v73
	v_mov_b32_dpp v77, v117 row_shr:1 row_mask:0xf bank_mask:0xf
	v_mov_b32_dpp v81, v93 row_ror:2 row_mask:0xf bank_mask:0xf bound_ctrl:1
	v_mul_f32_e32 v77, v209, v77
	v_fmac_f32_e32 v77, v207, v117
	v_mov_b32_dpp v81, v117 row_shr:2 row_mask:0xf bank_mask:0xf
	v_fmac_f32_e32 v77, v203, v81
	v_add_f32_e32 v77, v205, v77
	v_mul_f32_e32 v81, 0xbfb8aa3b, v77
	v_exp_f32_e32 v81, v81
	v_mov_b32_dpp v109, v89 row_ror:1 row_mask:0xf bank_mask:0xf bound_ctrl:1
	v_mov_b32_dpp v149, v89 row_ror:2 row_mask:0xf bank_mask:0xf bound_ctrl:1
	v_add_f32_e32 v81, 1.0, v81
	v_mov_b32_dpp v109, v113 row_shr:1 row_mask:0xf bank_mask:0xf
	v_rcp_f32_e32 v81, v81
	v_mul_f32_e32 v109, v201, v109
	v_mov_b32_dpp v149, v113 row_shr:2 row_mask:0xf bank_mask:0xf
	v_fmac_f32_e32 v109, v113, v197
	v_fmac_f32_e32 v109, v177, v149
	v_add_f32_e32 v109, v199, v109
	v_mul_f32_e32 v77, v77, v81
	v_mul_f32_e32 v77, v109, v77
	v_cvt_pk_bf16_f32 v172, v73, v77
	v_mov_b32_dpp v73, v116 row_ror:1 row_mask:0xf bank_mask:0xf bound_ctrl:1
	s_nop 0
	v_mov_b32_dpp v77, v116 row_ror:2 row_mask:0xf bank_mask:0xf bound_ctrl:1
	v_mov_b32_dpp v81, v112 row_ror:1 row_mask:0xf bank_mask:0xf bound_ctrl:1
	v_mov_b32_dpp v73, v104 row_shr:1 row_mask:0xf bank_mask:0xf
	v_mul_f32_e32 v73, v208, v73
	v_mov_b32_dpp v77, v104 row_shr:2 row_mask:0xf bank_mask:0xf
	v_fmac_f32_e32 v73, v206, v104
	v_fmac_f32_e32 v73, v202, v77
	v_add_f32_e32 v73, v204, v73
	v_mul_f32_e32 v77, 0xbfb8aa3b, v73
	v_exp_f32_e32 v77, v77
	v_mov_b32_dpp v81, v84 row_shr:1 row_mask:0xf bank_mask:0xf
	v_mov_b32_dpp v109, v112 row_ror:2 row_mask:0xf bank_mask:0xf bound_ctrl:1
	v_mul_f32_e32 v81, v200, v81
	v_add_f32_e32 v77, 1.0, v77
	v_rcp_f32_e32 v77, v77
	v_mov_b32_dpp v109, v84 row_shr:2 row_mask:0xf bank_mask:0xf
	v_fmac_f32_e32 v81, v84, v196
	v_fmac_f32_e32 v81, v176, v109
	v_mul_f32_e32 v73, v73, v77
	v_mov_b32_dpp v77, v117 row_ror:1 row_mask:0xf bank_mask:0xf bound_ctrl:1
	v_add_f32_e32 v81, v198, v81
	v_mul_f32_e32 v73, v81, v73
	v_mov_b32_dpp v77, v105 row_shr:1 row_mask:0xf bank_mask:0xf
	v_mov_b32_dpp v81, v117 row_ror:2 row_mask:0xf bank_mask:0xf bound_ctrl:1
	v_mul_f32_e32 v77, v209, v77
	v_fmac_f32_e32 v77, v207, v105
	v_mov_b32_dpp v81, v105 row_shr:2 row_mask:0xf bank_mask:0xf
	v_fmac_f32_e32 v77, v203, v81
	v_add_f32_e32 v77, v205, v77
	v_mul_f32_e32 v81, 0xbfb8aa3b, v77
	v_exp_f32_e32 v81, v81
	v_mov_b32_dpp v109, v113 row_ror:1 row_mask:0xf bank_mask:0xf bound_ctrl:1
	v_mov_b32_dpp v112, v113 row_ror:2 row_mask:0xf bank_mask:0xf bound_ctrl:1
	v_add_f32_e32 v81, 1.0, v81
	v_mov_b32_dpp v109, v85 row_shr:1 row_mask:0xf bank_mask:0xf
	v_rcp_f32_e32 v81, v81
	v_mul_f32_e32 v109, v201, v109
	v_mov_b32_dpp v112, v85 row_shr:2 row_mask:0xf bank_mask:0xf
	v_fmac_f32_e32 v109, v85, v197
	v_fmac_f32_e32 v109, v177, v112
	v_add_f32_e32 v109, v199, v109
	v_mul_f32_e32 v77, v77, v81
	v_mul_f32_e32 v77, v109, v77
	v_cvt_pk_bf16_f32 v174, v73, v77
	v_mov_b32_dpp v73, v104 row_ror:1 row_mask:0xf bank_mask:0xf bound_ctrl:1
	s_nop 0
	v_mov_b32_dpp v77, v104 row_ror:2 row_mask:0xf bank_mask:0xf bound_ctrl:1
	v_mov_b32_dpp v81, v84 row_ror:1 row_mask:0xf bank_mask:0xf bound_ctrl:1
	v_mov_b32_dpp v73, v68 row_shr:1 row_mask:0xf bank_mask:0xf
	v_mul_f32_e32 v73, v208, v73
	v_mov_b32_dpp v77, v68 row_shr:2 row_mask:0xf bank_mask:0xf
	v_fmac_f32_e32 v73, v206, v68
	v_fmac_f32_e32 v73, v202, v77
	v_add_f32_e32 v73, v204, v73
	v_mul_f32_e32 v77, 0xbfb8aa3b, v73
	v_exp_f32_e32 v77, v77
	v_mov_b32_dpp v81, v64 row_shr:1 row_mask:0xf bank_mask:0xf
	v_mov_b32_dpp v84, v84 row_ror:2 row_mask:0xf bank_mask:0xf bound_ctrl:1
	v_mul_f32_e32 v81, v200, v81
	v_add_f32_e32 v77, 1.0, v77
	v_rcp_f32_e32 v77, v77
	v_mov_b32_dpp v84, v64 row_shr:2 row_mask:0xf bank_mask:0xf
	v_fmac_f32_e32 v81, v196, v64
	v_fmac_f32_e32 v81, v176, v84
	v_mul_f32_e32 v73, v73, v77
	v_mov_b32_dpp v77, v105 row_ror:1 row_mask:0xf bank_mask:0xf bound_ctrl:1
	v_add_f32_e32 v81, v198, v81
	v_mul_f32_e32 v73, v81, v73
	v_mov_b32_dpp v77, v69 row_shr:1 row_mask:0xf bank_mask:0xf
	v_mov_b32_dpp v81, v105 row_ror:2 row_mask:0xf bank_mask:0xf bound_ctrl:1
	v_mul_f32_e32 v77, v209, v77
	v_fmac_f32_e32 v77, v207, v69
	v_mov_b32_dpp v81, v69 row_shr:2 row_mask:0xf bank_mask:0xf
	v_fmac_f32_e32 v77, v203, v81
	v_add_f32_e32 v77, v205, v77
	v_mul_f32_e32 v81, 0xbfb8aa3b, v77
	v_exp_f32_e32 v81, v81
	v_mov_b32_dpp v84, v85 row_ror:1 row_mask:0xf bank_mask:0xf bound_ctrl:1
	v_mov_b32_dpp v85, v85 row_ror:2 row_mask:0xf bank_mask:0xf bound_ctrl:1
	v_add_f32_e32 v81, 1.0, v81
	v_mov_b32_dpp v84, v65 row_shr:1 row_mask:0xf bank_mask:0xf
	v_rcp_f32_e32 v81, v81
	v_mul_f32_e32 v84, v201, v84
	v_mov_b32_dpp v85, v65 row_shr:2 row_mask:0xf bank_mask:0xf
	v_fmac_f32_e32 v84, v197, v65
	v_fmac_f32_e32 v84, v177, v85
	v_add_f32_e32 v84, v199, v84
	v_mul_f32_e32 v77, v77, v81
	v_mul_f32_e32 v77, v84, v77
	v_cvt_pk_bf16_f32 v176, v73, v77
	s_waitcnt vmcnt(6)
	s_nop 0
	v_mul_f32_dpp v77, v126, v192 row_shr:1 row_mask:0xf bank_mask:0xf bound_ctrl:1
	v_mov_b32_dpp v73, v126 row_shr:2 row_mask:0xf bank_mask:0xf bound_ctrl:1
	s_waitcnt vmcnt(5)
	v_fmac_f32_e32 v77, v126, v190
	v_fmac_f32_e32 v77, v186, v73
	s_waitcnt vmcnt(4)
	v_add_f32_e32 v73, v188, v77
	v_mul_f32_e32 v77, 0xbfb8aa3b, v73
	v_exp_f32_e32 v77, v77
	s_waitcnt vmcnt(2)
	v_mul_f32_dpp v84, v122, v184 row_shr:1 row_mask:0xf bank_mask:0xf bound_ctrl:1
	v_mov_b32_dpp v81, v122 row_shr:2 row_mask:0xf bank_mask:0xf bound_ctrl:1
	s_waitcnt vmcnt(1)
	v_fmac_f32_e32 v84, v122, v180
	v_add_f32_e32 v77, 1.0, v77
	v_rcp_f32_e32 v77, v77
	v_fmac_f32_e32 v84, v178, v81
	s_waitcnt vmcnt(0)
	v_add_f32_e32 v81, v182, v84
	v_mul_f32_dpp v85, v123, v185 row_shr:1 row_mask:0xf bank_mask:0xf bound_ctrl:1
	v_mul_f32_dpp v84, v127, v193 row_shr:1 row_mask:0xf bank_mask:0xf bound_ctrl:1
	v_mul_f32_e32 v73, v73, v77
	v_mov_b32_dpp v77, v127 row_shr:2 row_mask:0xf bank_mask:0xf bound_ctrl:1
	v_fmac_f32_e32 v84, v127, v191
	v_fmac_f32_e32 v84, v187, v77
	v_add_f32_e32 v77, v189, v84
	v_mul_f32_e32 v84, 0xbfb8aa3b, v77
	v_exp_f32_e32 v84, v84
	v_mul_f32_e32 v73, v81, v73
	v_mov_b32_dpp v81, v123 row_shr:2 row_mask:0xf bank_mask:0xf bound_ctrl:1
	v_fmac_f32_e32 v85, v123, v181
	v_add_f32_e32 v84, 1.0, v84
	v_rcp_f32_e32 v84, v84
	v_fmac_f32_e32 v85, v179, v81
	v_add_f32_e32 v81, v183, v85
	v_mul_f32_e32 v77, v77, v84
	v_mul_f32_e32 v77, v81, v77
	v_cvt_pk_bf16_f32 v81, v73, v77
	s_and_saveexec_b64 s[56:57], s[2:3]
	s_xor_b64 s[56:57], exec, s[56:57]
	s_cbranch_execz .LBB0_1214
	v_mov_b64_e32 v[84:85], s[48:49]
	v_mad_i64_i32 v[84:85], s[58:59], v156, s85, v[84:85]
	v_lshl_add_u64 v[84:85], v[146:147], 1, v[84:85]
	v_mov_b32_e32 v251, v80
	v_mov_b32_e32 v252, v81

.LBB0_1219:
	s_or_b64 exec, exec, s[56:57]
	s_addk_i32 s51, 0x80
	v_or_b32_e32 v72, 16, v146
	v_pk_mul_f32 v[94:95], v[94:95], v[154:155] op_sel_hi:[1,0]
	v_pk_mul_f32 v[90:91], v[90:91], v[154:155] op_sel_hi:[1,0]
	v_or_b32_e32 v157, s51, v210
	v_ashrrev_i32_e32 v73, 31, v72
	v_lshlrev_b64 v[96:97], 2, v[72:73]
	v_lshl_add_u64 v[98:99], s[16:17], 0, v[96:97]
	v_lshl_add_u64 v[100:101], s[8:9], 0, v[96:97]
	v_lshl_add_u64 v[102:103], s[24:25], 0, v[96:97]
	global_load_dwordx2 v[110:111], v[98:99], off
	global_load_dwordx2 v[116:117], v[100:101], off
	global_load_dwordx2 v[114:115], v[102:103], off
	v_lshl_add_u64 v[98:99], s[18:19], 0, v[96:97]
	global_load_dwordx2 v[112:113], v[98:99], off
	v_lshl_add_u64 v[98:99], s[26:27], 0, v[96:97]
	v_lshl_add_u64 v[100:101], s[28:29], 0, v[96:97]
	v_lshl_add_u64 v[102:103], s[30:31], 0, v[96:97]
	global_load_dwordx2 v[98:99], v[98:99], off
	s_nop 0
	global_load_dwordx2 v[108:109], v[100:101], off
	s_nop 0
	global_load_dwordx2 v[100:101], v[102:103], off
	v_lshl_add_u64 v[96:97], s[42:43], 0, v[96:97]
	global_load_dwordx2 v[102:103], v[96:97], off
	v_mul_f32_dpp v151, v90, v184 row_shr:1 row_mask:0xf bank_mask:0xf bound_ctrl:1
	v_mul_f32_dpp v97, v94, v192 row_shr:1 row_mask:0xf bank_mask:0xf bound_ctrl:1
	v_mov_b32_dpp v96, v94 row_shr:2 row_mask:0xf bank_mask:0xf bound_ctrl:1
	v_fmac_f32_e32 v97, v94, v190
	v_fmac_f32_e32 v97, v186, v96
	v_add_f32_e32 v96, v188, v97
	v_mul_f32_e32 v97, 0xbfb8aa3b, v96
	v_exp_f32_e32 v97, v97
	v_mov_b32_dpp v149, v90 row_shr:2 row_mask:0xf bank_mask:0xf bound_ctrl:1
	v_fmac_f32_e32 v151, v90, v180
	v_fmac_f32_e32 v151, v178, v149
	v_add_f32_e32 v97, 1.0, v97
	v_rcp_f32_e32 v97, v97
	v_add_f32_e32 v149, v182, v151
	v_mul_f32_dpp v151, v95, v193 row_shr:1 row_mask:0xf bank_mask:0xf bound_ctrl:1
	v_fmac_f32_e32 v151, v95, v191
	v_mul_f32_e32 v96, v96, v97
	v_mov_b32_dpp v97, v95 row_shr:2 row_mask:0xf bank_mask:0xf bound_ctrl:1
	v_fmac_f32_e32 v151, v187, v97
	v_add_f32_e32 v97, v189, v151
	v_mul_f32_e32 v151, 0xbfb8aa3b, v97
	v_exp_f32_e32 v151, v151
	v_mul_f32_dpp v153, v91, v185 row_shr:1 row_mask:0xf bank_mask:0xf bound_ctrl:1
	v_mul_f32_e32 v96, v149, v96
	v_mov_b32_dpp v149, v91 row_shr:2 row_mask:0xf bank_mask:0xf bound_ctrl:1
	v_add_f32_e32 v151, 1.0, v151
	v_rcp_f32_e32 v151, v151
	v_fmac_f32_e32 v153, v91, v181
	v_fmac_f32_e32 v153, v179, v149
	v_add_f32_e32 v149, v183, v153
	v_mul_f32_e32 v97, v97, v151
	v_mul_f32_e32 v97, v149, v97
	v_cvt_pk_bf16_f32 v195, v96, v97
	s_and_saveexec_b64 s[56:57], s[2:3]
	s_xor_b64 s[56:57], exec, s[56:57]
	s_cbranch_execz .LBB0_1221
	v_mov_b64_e32 v[96:97], s[48:49]
	v_mad_i64_i32 v[96:97], s[58:59], v157, s85, v[96:97]
	v_lshl_add_u64 v[96:97], v[146:147], 1, v[96:97]
	v_mov_b32_e32 v253, v194
	v_mov_b32_e32 v254, v195

.LBB0_1226:
	s_or_b64 exec, exec, s[56:57]
	v_mov_b32_e32 v165, v164
	v_mov_b32_e32 v163, v162
	v_mov_b32_e32 v161, v160
	v_mov_b32_e32 v159, v158
	v_mov_b32_e32 v155, v154
	v_mov_b32_e32 v153, v152
	v_mov_b32_e32 v151, v150
	v_mov_b32_e32 v149, v148
	v_mov_b32_e32 v64, v164
	v_mov_b32_e32 v65, v164
	v_pk_mul_f32 v[62:63], v[62:63], v[64:65]
	v_pk_mul_f32 v[60:61], v[60:61], v[164:165]
	v_pk_mul_f32 v[58:59], v[58:59], v[64:65]
	v_pk_mul_f32 v[56:57], v[56:57], v[164:165]
	v_pk_mul_f32 v[52:53], v[52:53], v[162:163]
	v_pk_mul_f32 v[64:65], v[44:45], v[162:163]
	v_pk_mul_f32 v[48:49], v[48:49], v[160:161]
	v_pk_mul_f32 v[44:45], v[36:37], v[160:161]
	v_pk_mul_f32 v[36:37], v[40:41], v[158:159]
	v_pk_mul_f32 v[32:33], v[32:33], v[158:159]
	v_pk_mul_f32 v[28:29], v[28:29], v[154:155]
	v_pk_mul_f32 v[24:25], v[24:25], v[154:155]
	v_pk_mul_f32 v[120:121], v[20:21], v[152:153]
	v_pk_mul_f32 v[12:13], v[12:13], v[152:153]
	v_pk_mul_f32 v[20:21], v[4:5], v[150:151]
	v_pk_mul_f32 v[4:5], v[8:9], v[148:149]
	v_pk_mul_f32 v[0:1], v[0:1], v[148:149]
	v_pk_mul_f32 v[118:119], v[16:17], v[150:151]
	s_waitcnt vmcnt(5)
	v_mul_f32_dpp v16, v60, v116 row_shr:1 row_mask:0xf bank_mask:0xf bound_ctrl:1
	v_mov_b32_dpp v9, v60 row_shr:2 row_mask:0xf bank_mask:0xf bound_ctrl:1
	s_waitcnt vmcnt(4)
	v_fmac_f32_e32 v16, v60, v114
	v_fmac_f32_e32 v16, v110, v9
	s_waitcnt vmcnt(3)
	v_add_f32_e32 v16, v112, v16
	v_mul_f32_e32 v9, 0xbfb8aa3b, v16
	v_exp_f32_e32 v17, v9
	s_waitcnt vmcnt(1)
	v_mul_f32_dpp v41, v56, v108 row_shr:1 row_mask:0xf bank_mask:0xf bound_ctrl:1
	v_mov_b32_dpp v40, v56 row_shr:2 row_mask:0xf bank_mask:0xf bound_ctrl:1
	s_waitcnt vmcnt(0)
	v_fmac_f32_e32 v41, v56, v100
	v_add_f32_e32 v17, 1.0, v17
	v_rcp_f32_e32 v17, v17
	v_fmac_f32_e32 v41, v98, v40
	s_waitcnt vmcnt(0)
	v_add_f32_e32 v40, v102, v41
	v_mul_f32_dpp v66, v57, v109 row_shr:1 row_mask:0xf bank_mask:0xf bound_ctrl:1
	v_mul_f32_dpp v41, v61, v117 row_shr:1 row_mask:0xf bank_mask:0xf bound_ctrl:1
	v_mul_f32_e32 v16, v16, v17
	v_mov_b32_dpp v17, v61 row_shr:2 row_mask:0xf bank_mask:0xf bound_ctrl:1
	v_fmac_f32_e32 v41, v61, v115
	v_fmac_f32_e32 v41, v111, v17
	v_add_f32_e32 v17, v113, v41
	v_mul_f32_e32 v41, 0xbfb8aa3b, v17
	v_exp_f32_e32 v41, v41
	v_mul_f32_e32 v16, v40, v16
	v_mov_b32_dpp v40, v57 row_shr:2 row_mask:0xf bank_mask:0xf bound_ctrl:1
	v_fmac_f32_e32 v66, v57, v101
	v_add_f32_e32 v41, 1.0, v41
	v_rcp_f32_e32 v41, v41
	v_fmac_f32_e32 v66, v99, v40
	v_add_f32_e32 v40, v103, v66
	v_or_b32_e32 v8, 18, v146
	v_mul_f32_e32 v17, v17, v41
	v_mul_f32_e32 v17, v40, v17
	v_cvt_pk_bf16_f32 v94, v16, v17
	v_ashrrev_i32_e32 v9, 31, v8
	v_mov_b32_dpp v16, v60 row_ror:1 row_mask:0xf bank_mask:0xf bound_ctrl:1
	v_mov_b32_dpp v17, v60 row_ror:2 row_mask:0xf bank_mask:0xf bound_ctrl:1
	v_mov_b32_dpp v40, v56 row_ror:1 row_mask:0xf bank_mask:0xf bound_ctrl:1
	v_mov_b32_dpp v16, v52 row_shr:1 row_mask:0xf bank_mask:0xf
	v_mul_f32_e32 v16, v116, v16
	v_mov_b32_dpp v17, v52 row_shr:2 row_mask:0xf bank_mask:0xf
	v_fmac_f32_e32 v16, v52, v114
	v_fmac_f32_e32 v16, v110, v17
	v_add_f32_e32 v16, v112, v16
	v_mul_f32_e32 v17, 0xbfb8aa3b, v16
	v_exp_f32_e32 v17, v17
	v_mov_b32_dpp v40, v64 row_shr:1 row_mask:0xf bank_mask:0xf
	v_mov_b32_dpp v41, v56 row_ror:2 row_mask:0xf bank_mask:0xf bound_ctrl:1
	v_mul_f32_e32 v40, v108, v40
	v_add_f32_e32 v17, 1.0, v17
	v_rcp_f32_e32 v17, v17
	v_mov_b32_dpp v41, v64 row_shr:2 row_mask:0xf bank_mask:0xf
	v_fmac_f32_e32 v40, v64, v100
	v_fmac_f32_e32 v40, v98, v41
	v_mul_f32_e32 v16, v16, v17
	v_mov_b32_dpp v17, v61 row_ror:1 row_mask:0xf bank_mask:0xf bound_ctrl:1
	v_add_f32_e32 v40, v102, v40
	v_mul_f32_e32 v16, v40, v16
	v_mov_b32_dpp v17, v53 row_shr:1 row_mask:0xf bank_mask:0xf
	v_mov_b32_dpp v40, v61 row_ror:2 row_mask:0xf bank_mask:0xf bound_ctrl:1
	v_mul_f32_e32 v17, v117, v17
	v_fmac_f32_e32 v17, v53, v115
	v_mov_b32_dpp v40, v53 row_shr:2 row_mask:0xf bank_mask:0xf
	v_fmac_f32_e32 v17, v111, v40
	v_add_f32_e32 v17, v113, v17
	v_mul_f32_e32 v40, 0xbfb8aa3b, v17
	v_exp_f32_e32 v40, v40
	v_mov_b32_dpp v41, v57 row_ror:1 row_mask:0xf bank_mask:0xf bound_ctrl:1
	v_mov_b32_dpp v66, v57 row_ror:2 row_mask:0xf bank_mask:0xf bound_ctrl:1
	v_add_f32_e32 v40, 1.0, v40
	v_mov_b32_dpp v41, v65 row_shr:1 row_mask:0xf bank_mask:0xf
	v_rcp_f32_e32 v40, v40
	v_mul_f32_e32 v41, v109, v41
	v_mov_b32_dpp v66, v65 row_shr:2 row_mask:0xf bank_mask:0xf
	v_fmac_f32_e32 v41, v65, v101
	v_fmac_f32_e32 v41, v99, v66
	v_add_f32_e32 v41, v103, v41
	v_mul_f32_e32 v17, v17, v40
	v_mul_f32_e32 v17, v41, v17
	v_cvt_pk_bf16_f32 v88, v16, v17
	v_mov_b32_dpp v16, v52 row_ror:1 row_mask:0xf bank_mask:0xf bound_ctrl:1
	s_nop 0
	v_mov_b32_dpp v17, v52 row_ror:2 row_mask:0xf bank_mask:0xf bound_ctrl:1
	v_mov_b32_dpp v40, v64 row_ror:1 row_mask:0xf bank_mask:0xf bound_ctrl:1
	v_mov_b32_dpp v16, v48 row_shr:1 row_mask:0xf bank_mask:0xf
	v_mul_f32_e32 v16, v116, v16
	v_mov_b32_dpp v17, v48 row_shr:2 row_mask:0xf bank_mask:0xf
	v_fmac_f32_e32 v16, v48, v114
	v_fmac_f32_e32 v16, v110, v17
	v_add_f32_e32 v16, v112, v16
	v_mul_f32_e32 v17, 0xbfb8aa3b, v16
	v_exp_f32_e32 v17, v17
	v_mov_b32_dpp v40, v44 row_shr:1 row_mask:0xf bank_mask:0xf
	v_mov_b32_dpp v41, v64 row_ror:2 row_mask:0xf bank_mask:0xf bound_ctrl:1
	v_mul_f32_e32 v40, v108, v40
	v_add_f32_e32 v17, 1.0, v17
	v_rcp_f32_e32 v17, v17
	v_mov_b32_dpp v41, v44 row_shr:2 row_mask:0xf bank_mask:0xf
	v_fmac_f32_e32 v40, v44, v100
	v_fmac_f32_e32 v40, v98, v41
	v_mul_f32_e32 v16, v16, v17
	v_mov_b32_dpp v17, v53 row_ror:1 row_mask:0xf bank_mask:0xf bound_ctrl:1
	v_add_f32_e32 v40, v102, v40
	v_mul_f32_e32 v16, v40, v16
	v_mov_b32_dpp v17, v49 row_shr:1 row_mask:0xf bank_mask:0xf
	v_mov_b32_dpp v40, v53 row_ror:2 row_mask:0xf bank_mask:0xf bound_ctrl:1
	v_mul_f32_e32 v17, v117, v17
	v_fmac_f32_e32 v17, v49, v115
	v_mov_b32_dpp v40, v49 row_shr:2 row_mask:0xf bank_mask:0xf
	v_fmac_f32_e32 v17, v111, v40
	v_add_f32_e32 v17, v113, v17
	v_mul_f32_e32 v40, 0xbfb8aa3b, v17
	v_exp_f32_e32 v40, v40
	v_mov_b32_dpp v41, v65 row_ror:1 row_mask:0xf bank_mask:0xf bound_ctrl:1
	v_mov_b32_dpp v52, v65 row_ror:2 row_mask:0xf bank_mask:0xf bound_ctrl:1
	v_add_f32_e32 v40, 1.0, v40
	v_mov_b32_dpp v41, v45 row_shr:1 row_mask:0xf bank_mask:0xf
	v_rcp_f32_e32 v40, v40
	v_mul_f32_e32 v41, v109, v41
	v_mov_b32_dpp v52, v45 row_shr:2 row_mask:0xf bank_mask:0xf
	v_fmac_f32_e32 v41, v45, v101
	v_fmac_f32_e32 v41, v99, v52
	v_add_f32_e32 v41, v103, v41
	v_mul_f32_e32 v17, v17, v40
	v_mul_f32_e32 v17, v41, v17
	v_cvt_pk_bf16_f32 v90, v16, v17
	v_mov_b32_dpp v16, v48 row_ror:1 row_mask:0xf bank_mask:0xf bound_ctrl:1
	s_nop 0
	v_mov_b32_dpp v17, v48 row_ror:2 row_mask:0xf bank_mask:0xf bound_ctrl:1
	v_mov_b32_dpp v40, v44 row_ror:1 row_mask:0xf bank_mask:0xf bound_ctrl:1
	v_mov_b32_dpp v16, v36 row_shr:1 row_mask:0xf bank_mask:0xf
	v_mul_f32_e32 v16, v116, v16
	v_mov_b32_dpp v17, v36 row_shr:2 row_mask:0xf bank_mask:0xf
	v_fmac_f32_e32 v16, v36, v114
	v_fmac_f32_e32 v16, v110, v17
	v_add_f32_e32 v16, v112, v16
	v_mul_f32_e32 v17, 0xbfb8aa3b, v16
	v_exp_f32_e32 v17, v17
	v_mov_b32_dpp v40, v32 row_shr:1 row_mask:0xf bank_mask:0xf
	v_mov_b32_dpp v41, v44 row_ror:2 row_mask:0xf bank_mask:0xf bound_ctrl:1
	v_mul_f32_e32 v40, v108, v40
	v_add_f32_e32 v17, 1.0, v17
	v_rcp_f32_e32 v17, v17
	v_mov_b32_dpp v41, v32 row_shr:2 row_mask:0xf bank_mask:0xf
	v_fmac_f32_e32 v40, v32, v100
	v_fmac_f32_e32 v40, v98, v41
	v_mul_f32_e32 v16, v16, v17
	v_mov_b32_dpp v17, v49 row_ror:1 row_mask:0xf bank_mask:0xf bound_ctrl:1
	v_add_f32_e32 v40, v102, v40
	v_mul_f32_e32 v16, v40, v16
	v_mov_b32_dpp v17, v37 row_shr:1 row_mask:0xf bank_mask:0xf
	v_mov_b32_dpp v40, v49 row_ror:2 row_mask:0xf bank_mask:0xf bound_ctrl:1
	v_mul_f32_e32 v17, v117, v17
	v_fmac_f32_e32 v17, v37, v115
	v_mov_b32_dpp v40, v37 row_shr:2 row_mask:0xf bank_mask:0xf
	v_fmac_f32_e32 v17, v111, v40
	v_add_f32_e32 v17, v113, v17
	v_mul_f32_e32 v40, 0xbfb8aa3b, v17
	v_exp_f32_e32 v40, v40
	v_mov_b32_dpp v41, v45 row_ror:1 row_mask:0xf bank_mask:0xf bound_ctrl:1
	v_mov_b32_dpp v44, v45 row_ror:2 row_mask:0xf bank_mask:0xf bound_ctrl:1
	v_add_f32_e32 v40, 1.0, v40
	v_mov_b32_dpp v41, v33 row_shr:1 row_mask:0xf bank_mask:0xf
	v_rcp_f32_e32 v40, v40
	v_mul_f32_e32 v41, v109, v41
	v_mov_b32_dpp v44, v33 row_shr:2 row_mask:0xf bank_mask:0xf
	v_fmac_f32_e32 v41, v33, v101
	v_fmac_f32_e32 v41, v99, v44
	v_add_f32_e32 v41, v103, v41
	v_mul_f32_e32 v17, v17, v40
	v_mul_f32_e32 v17, v41, v17
	v_cvt_pk_bf16_f32 v92, v16, v17
	v_lshlrev_b64 v[8:9], 2, v[8:9]
	v_lshl_add_u64 v[16:17], s[16:17], 0, v[8:9]
	v_lshl_add_u64 v[40:41], s[8:9], 0, v[8:9]
	v_lshl_add_u64 v[44:45], s[24:25], 0, v[8:9]
	global_load_dwordx2 v[52:53], v[16:17], off
	global_load_dwordx2 v[68:69], v[40:41], off
	global_load_dwordx2 v[66:67], v[44:45], off
	v_lshl_add_u64 v[16:17], s[18:19], 0, v[8:9]
	global_load_dwordx2 v[64:65], v[16:17], off
	v_lshl_add_u64 v[16:17], s[26:27], 0, v[8:9]
	v_lshl_add_u64 v[40:41], s[28:29], 0, v[8:9]
	v_lshl_add_u64 v[44:45], s[30:31], 0, v[8:9]
	global_load_dwordx2 v[16:17], v[16:17], off
	s_nop 0
	global_load_dwordx2 v[48:49], v[40:41], off
	s_nop 0
	global_load_dwordx2 v[40:41], v[44:45], off
	v_lshl_add_u64 v[8:9], s[42:43], 0, v[8:9]
	global_load_dwordx2 v[44:45], v[8:9], off
	v_mul_f32_dpp v71, v24, v108 row_shr:1 row_mask:0xf bank_mask:0xf bound_ctrl:1
	v_mul_f32_dpp v9, v28, v116 row_shr:1 row_mask:0xf bank_mask:0xf bound_ctrl:1
	v_mov_b32_dpp v8, v28 row_shr:2 row_mask:0xf bank_mask:0xf bound_ctrl:1
	v_fmac_f32_e32 v9, v28, v114
	v_fmac_f32_e32 v9, v110, v8
	v_add_f32_e32 v8, v112, v9
	v_mul_f32_e32 v9, 0xbfb8aa3b, v8
	v_exp_f32_e32 v9, v9
	v_mov_b32_dpp v70, v24 row_shr:2 row_mask:0xf bank_mask:0xf bound_ctrl:1
	v_fmac_f32_e32 v71, v24, v100
	v_fmac_f32_e32 v71, v98, v70
	v_add_f32_e32 v9, 1.0, v9
	v_rcp_f32_e32 v9, v9
	v_add_f32_e32 v70, v102, v71
	v_mul_f32_dpp v71, v29, v117 row_shr:1 row_mask:0xf bank_mask:0xf bound_ctrl:1
	v_fmac_f32_e32 v71, v29, v115
	v_mul_f32_e32 v8, v8, v9
	v_mov_b32_dpp v9, v29 row_shr:2 row_mask:0xf bank_mask:0xf bound_ctrl:1
	v_fmac_f32_e32 v71, v111, v9
	v_add_f32_e32 v9, v113, v71
	v_mul_f32_e32 v71, 0xbfb8aa3b, v9
	v_exp_f32_e32 v71, v71
	v_mul_f32_dpp v89, v25, v109 row_shr:1 row_mask:0xf bank_mask:0xf bound_ctrl:1
	v_mul_f32_e32 v8, v70, v8
	v_mov_b32_dpp v70, v25 row_shr:2 row_mask:0xf bank_mask:0xf bound_ctrl:1
	v_add_f32_e32 v71, 1.0, v71
	v_rcp_f32_e32 v71, v71
	v_fmac_f32_e32 v89, v25, v101
	v_fmac_f32_e32 v89, v99, v70
	v_add_f32_e32 v70, v103, v89
	v_mul_f32_e32 v9, v9, v71
	v_mul_f32_e32 v9, v70, v9
	v_cvt_pk_bf16_f32 v70, v8, v9
	v_mov_b32_dpp v8, v28 row_ror:1 row_mask:0xf bank_mask:0xf bound_ctrl:1
	s_nop 0
	v_mov_b32_dpp v9, v28 row_ror:2 row_mask:0xf bank_mask:0xf bound_ctrl:1
	v_mov_b32_dpp v71, v24 row_ror:1 row_mask:0xf bank_mask:0xf bound_ctrl:1
	v_mov_b32_dpp v8, v120 row_shr:1 row_mask:0xf bank_mask:0xf
	v_mul_f32_e32 v8, v116, v8
	v_mov_b32_dpp v9, v120 row_shr:2 row_mask:0xf bank_mask:0xf
	v_fmac_f32_e32 v8, v120, v114
	v_fmac_f32_e32 v8, v110, v9
	v_add_f32_e32 v8, v112, v8
	v_mul_f32_e32 v9, 0xbfb8aa3b, v8
	v_exp_f32_e32 v9, v9
	v_mov_b32_dpp v71, v12 row_shr:1 row_mask:0xf bank_mask:0xf
	v_mov_b32_dpp v89, v24 row_ror:2 row_mask:0xf bank_mask:0xf bound_ctrl:1
	v_mul_f32_e32 v71, v108, v71
	v_add_f32_e32 v9, 1.0, v9
	v_rcp_f32_e32 v9, v9
	v_mov_b32_dpp v89, v12 row_shr:2 row_mask:0xf bank_mask:0xf
	v_fmac_f32_e32 v71, v12, v100
	v_fmac_f32_e32 v71, v98, v89
	v_mul_f32_e32 v8, v8, v9
	v_mov_b32_dpp v9, v29 row_ror:1 row_mask:0xf bank_mask:0xf bound_ctrl:1
	v_add_f32_e32 v71, v102, v71
	v_mul_f32_e32 v8, v71, v8
	v_mov_b32_dpp v9, v121 row_shr:1 row_mask:0xf bank_mask:0xf
	v_mov_b32_dpp v71, v29 row_ror:2 row_mask:0xf bank_mask:0xf bound_ctrl:1
	v_mul_f32_e32 v9, v117, v9
	v_fmac_f32_e32 v9, v121, v115
	v_mov_b32_dpp v71, v121 row_shr:2 row_mask:0xf bank_mask:0xf
	v_fmac_f32_e32 v9, v111, v71
	v_add_f32_e32 v9, v113, v9
	v_mul_f32_e32 v71, 0xbfb8aa3b, v9
	v_exp_f32_e32 v71, v71
	v_mov_b32_dpp v89, v25 row_ror:1 row_mask:0xf bank_mask:0xf bound_ctrl:1
	v_mov_b32_dpp v91, v25 row_ror:2 row_mask:0xf bank_mask:0xf bound_ctrl:1
	v_add_f32_e32 v71, 1.0, v71
	v_mov_b32_dpp v89, v13 row_shr:1 row_mask:0xf bank_mask:0xf
	v_rcp_f32_e32 v71, v71
	v_mul_f32_e32 v89, v109, v89
	v_mov_b32_dpp v91, v13 row_shr:2 row_mask:0xf bank_mask:0xf
	v_fmac_f32_e32 v89, v13, v101
	v_fmac_f32_e32 v89, v99, v91
	v_add_f32_e32 v89, v103, v89
	v_mul_f32_e32 v9, v9, v71
	v_mul_f32_e32 v9, v89, v9
	v_cvt_pk_bf16_f32 v8, v8, v9
	s_nop 1
	v_mov_b32_dpp v9, v120 row_ror:1 row_mask:0xf bank_mask:0xf bound_ctrl:1
	v_mov_b32_dpp v71, v120 row_ror:2 row_mask:0xf bank_mask:0xf bound_ctrl:1
	v_mov_b32_dpp v89, v12 row_ror:1 row_mask:0xf bank_mask:0xf bound_ctrl:1
	v_mov_b32_dpp v9, v118 row_shr:1 row_mask:0xf bank_mask:0xf
	v_mul_f32_e32 v9, v116, v9
	v_mov_b32_dpp v71, v118 row_shr:2 row_mask:0xf bank_mask:0xf
	v_fmac_f32_e32 v9, v118, v114
	v_fmac_f32_e32 v9, v110, v71
	v_add_f32_e32 v9, v112, v9
	v_mul_f32_e32 v71, 0xbfb8aa3b, v9
	v_exp_f32_e32 v71, v71
	v_mov_b32_dpp v89, v20 row_shr:1 row_mask:0xf bank_mask:0xf
	v_mov_b32_dpp v12, v12 row_ror:2 row_mask:0xf bank_mask:0xf bound_ctrl:1
	v_mul_f32_e32 v89, v108, v89
	v_add_f32_e32 v71, 1.0, v71
	v_rcp_f32_e32 v71, v71
	v_mov_b32_dpp v12, v20 row_shr:2 row_mask:0xf bank_mask:0xf
	v_fmac_f32_e32 v89, v20, v100
	v_fmac_f32_e32 v89, v98, v12
	v_add_f32_e32 v12, v102, v89
	v_mul_f32_e32 v9, v9, v71
	v_mul_f32_e32 v9, v12, v9
	v_mov_b32_dpp v12, v121 row_ror:1 row_mask:0xf bank_mask:0xf bound_ctrl:1
	v_mov_b32_dpp v71, v121 row_ror:2 row_mask:0xf bank_mask:0xf bound_ctrl:1
	v_mov_b32_dpp v89, v13 row_ror:1 row_mask:0xf bank_mask:0xf bound_ctrl:1
	v_mov_b32_dpp v12, v119 row_shr:1 row_mask:0xf bank_mask:0xf
	v_mul_f32_e32 v12, v117, v12
	v_mov_b32_dpp v71, v119 row_shr:2 row_mask:0xf bank_mask:0xf
	v_fmac_f32_e32 v12, v119, v115
	v_fmac_f32_e32 v12, v111, v71
	v_add_f32_e32 v12, v113, v12
	v_mul_f32_e32 v71, 0xbfb8aa3b, v12
	v_exp_f32_e32 v71, v71
	v_mov_b32_dpp v89, v21 row_shr:1 row_mask:0xf bank_mask:0xf
	v_mov_b32_dpp v13, v13 row_ror:2 row_mask:0xf bank_mask:0xf bound_ctrl:1
	v_mul_f32_e32 v89, v109, v89
	v_add_f32_e32 v71, 1.0, v71
	v_rcp_f32_e32 v71, v71
	v_mov_b32_dpp v13, v21 row_shr:2 row_mask:0xf bank_mask:0xf
	v_fmac_f32_e32 v89, v21, v101
	v_fmac_f32_e32 v89, v99, v13
	v_add_f32_e32 v13, v103, v89
	v_mul_f32_e32 v12, v12, v71
	v_mul_f32_e32 v12, v13, v12
	v_cvt_pk_bf16_f32 v12, v9, v12
	v_mov_b32_dpp v9, v118 row_ror:1 row_mask:0xf bank_mask:0xf bound_ctrl:1
	v_mov_b32_dpp v13, v118 row_ror:2 row_mask:0xf bank_mask:0xf bound_ctrl:1
	v_mov_b32_dpp v71, v20 row_ror:1 row_mask:0xf bank_mask:0xf bound_ctrl:1
	v_mov_b32_dpp v9, v4 row_shr:1 row_mask:0xf bank_mask:0xf
	v_mul_f32_e32 v9, v116, v9
	v_mov_b32_dpp v13, v4 row_shr:2 row_mask:0xf bank_mask:0xf
	v_fmac_f32_e32 v9, v4, v114
	v_fmac_f32_e32 v9, v110, v13
	v_add_f32_e32 v9, v112, v9
	v_mul_f32_e32 v13, 0xbfb8aa3b, v9
	v_exp_f32_e32 v13, v13
	v_mov_b32_dpp v71, v0 row_shr:1 row_mask:0xf bank_mask:0xf
	v_mov_b32_dpp v20, v20 row_ror:2 row_mask:0xf bank_mask:0xf bound_ctrl:1
	v_mul_f32_e32 v71, v108, v71
	v_add_f32_e32 v13, 1.0, v13
	v_rcp_f32_e32 v13, v13
	v_mov_b32_dpp v20, v0 row_shr:2 row_mask:0xf bank_mask:0xf
	v_fmac_f32_e32 v71, v0, v100
	v_fmac_f32_e32 v71, v98, v20
	v_mul_f32_e32 v9, v9, v13
	v_mov_b32_dpp v13, v119 row_ror:1 row_mask:0xf bank_mask:0xf bound_ctrl:1
	v_add_f32_e32 v20, v102, v71
	v_mul_f32_e32 v9, v20, v9
	v_mov_b32_dpp v13, v5 row_shr:1 row_mask:0xf bank_mask:0xf
	v_mov_b32_dpp v20, v119 row_ror:2 row_mask:0xf bank_mask:0xf bound_ctrl:1
	v_mul_f32_e32 v13, v117, v13
	v_fmac_f32_e32 v13, v5, v115
	v_mov_b32_dpp v20, v5 row_shr:2 row_mask:0xf bank_mask:0xf
	v_fmac_f32_e32 v13, v111, v20
	v_add_f32_e32 v13, v113, v13
	v_mul_f32_e32 v20, 0xbfb8aa3b, v13
	v_exp_f32_e32 v20, v20
	v_mov_b32_dpp v71, v21 row_ror:1 row_mask:0xf bank_mask:0xf bound_ctrl:1
	v_mov_b32_dpp v21, v21 row_ror:2 row_mask:0xf bank_mask:0xf bound_ctrl:1
	v_add_f32_e32 v20, 1.0, v20
	v_mov_b32_dpp v71, v1 row_shr:1 row_mask:0xf bank_mask:0xf
	v_rcp_f32_e32 v20, v20
	v_mul_f32_e32 v71, v109, v71
	v_mov_b32_dpp v21, v1 row_shr:2 row_mask:0xf bank_mask:0xf
	v_fmac_f32_e32 v71, v1, v101
	v_fmac_f32_e32 v71, v99, v21
	v_add_f32_e32 v21, v103, v71
	v_mul_f32_e32 v13, v13, v20
	v_mul_f32_e32 v13, v21, v13
	v_cvt_pk_bf16_f32 v20, v9, v13
	s_waitcnt vmcnt(6)
	s_nop 0
	v_mul_f32_dpp v13, v62, v68 row_shr:1 row_mask:0xf bank_mask:0xf bound_ctrl:1
	v_mov_b32_dpp v9, v62 row_shr:2 row_mask:0xf bank_mask:0xf bound_ctrl:1
	s_waitcnt vmcnt(5)
	v_fmac_f32_e32 v13, v62, v66
	v_fmac_f32_e32 v13, v52, v9
	s_waitcnt vmcnt(4)
	v_add_f32_e32 v9, v64, v13
	v_mul_f32_e32 v13, 0xbfb8aa3b, v9
	v_exp_f32_e32 v13, v13
	s_waitcnt vmcnt(2)
	v_mul_f32_dpp v71, v58, v48 row_shr:1 row_mask:0xf bank_mask:0xf bound_ctrl:1
	v_mov_b32_dpp v21, v58 row_shr:2 row_mask:0xf bank_mask:0xf bound_ctrl:1
	s_waitcnt vmcnt(1)
	v_fmac_f32_e32 v71, v58, v40
	v_add_f32_e32 v13, 1.0, v13
	v_rcp_f32_e32 v13, v13
	v_fmac_f32_e32 v71, v16, v21
	s_waitcnt vmcnt(0)
	v_add_f32_e32 v21, v44, v71
	v_mul_f32_dpp v89, v59, v49 row_shr:1 row_mask:0xf bank_mask:0xf bound_ctrl:1
	v_mul_f32_dpp v71, v63, v69 row_shr:1 row_mask:0xf bank_mask:0xf bound_ctrl:1
	v_mul_f32_e32 v9, v9, v13
	v_mov_b32_dpp v13, v63 row_shr:2 row_mask:0xf bank_mask:0xf bound_ctrl:1
	v_fmac_f32_e32 v71, v63, v67
	v_fmac_f32_e32 v71, v53, v13
	v_add_f32_e32 v13, v65, v71
	v_mul_f32_e32 v71, 0xbfb8aa3b, v13
	v_exp_f32_e32 v71, v71
	v_mul_f32_e32 v9, v21, v9
	v_mov_b32_dpp v21, v59 row_shr:2 row_mask:0xf bank_mask:0xf bound_ctrl:1
	v_fmac_f32_e32 v89, v59, v41
	v_add_f32_e32 v71, 1.0, v71
	v_rcp_f32_e32 v71, v71
	v_fmac_f32_e32 v89, v17, v21
	v_add_f32_e32 v21, v45, v89
	v_mul_f32_e32 v13, v13, v71
	v_mul_f32_e32 v13, v21, v13
	v_cvt_pk_bf16_f32 v95, v9, v13
	s_and_saveexec_b64 s[56:57], s[2:3]
	s_xor_b64 s[56:57], exec, s[56:57]
	s_cbranch_execz .LBB0_1228
	v_mov_b64_e32 v[80:81], s[48:49]
	v_mad_i64_i32 v[80:81], s[58:59], v156, s85, v[80:81]
	v_lshl_add_u64 v[80:81], v[146:147], 1, v[80:81]
	v_mov_b32_e32 v232, v251
	v_mov_b32_e32 v233, v252
	v_mov_b32_e32 v234, v94
	v_mov_b32_e32 v235, v95
	s_nop 1
	v_permlane16_swap_b32_e32 v232, v234
	v_permlane16_swap_b32_e32 v233, v235
	v_lshl_add_u64 v[236:237], v[80:81], 0, v[238:239]
	global_store_dwordx4 v[236:237], v[232:235], off
	s_nop 1

.LBB0_1233:
	s_or_b64 exec, exec, s[56:57]
	v_mov_b32_e32 v155, v154
	v_pk_mul_f32 v[30:31], v[30:31], v[154:155]
	v_pk_mul_f32 v[26:27], v[26:27], v[154:155]
	s_nop 0
	v_mul_f32_dpp v13, v30, v68 row_shr:1 row_mask:0xf bank_mask:0xf bound_ctrl:1
	v_mov_b32_dpp v9, v30 row_shr:2 row_mask:0xf bank_mask:0xf bound_ctrl:1
	v_fmac_f32_e32 v13, v30, v66
	v_fmac_f32_e32 v13, v52, v9
	v_add_f32_e32 v9, v64, v13
	v_mul_f32_e32 v13, 0xbfb8aa3b, v9
	v_exp_f32_e32 v13, v13
	v_mul_f32_dpp v32, v26, v48 row_shr:1 row_mask:0xf bank_mask:0xf bound_ctrl:1
	v_mov_b32_dpp v21, v26 row_shr:2 row_mask:0xf bank_mask:0xf bound_ctrl:1
	v_fmac_f32_e32 v32, v26, v40
	v_add_f32_e32 v13, 1.0, v13
	v_rcp_f32_e32 v13, v13
	v_fmac_f32_e32 v32, v16, v21
	v_mul_f32_dpp v21, v31, v69 row_shr:1 row_mask:0xf bank_mask:0xf bound_ctrl:1
	v_fmac_f32_e32 v21, v31, v67
	v_mul_f32_e32 v9, v9, v13
	v_mov_b32_dpp v13, v31 row_shr:2 row_mask:0xf bank_mask:0xf bound_ctrl:1
	v_fmac_f32_e32 v21, v53, v13
	v_add_f32_e32 v13, v65, v21
	v_mul_f32_e32 v21, 0xbfb8aa3b, v13
	v_exp_f32_e32 v21, v21
	v_add_f32_e32 v16, v44, v32
	v_mul_f32_dpp v32, v27, v49 row_shr:1 row_mask:0xf bank_mask:0xf bound_ctrl:1
	v_mul_f32_e32 v9, v16, v9
	v_add_f32_e32 v21, 1.0, v21
	v_rcp_f32_e32 v21, v21
	v_mov_b32_dpp v16, v27 row_shr:2 row_mask:0xf bank_mask:0xf bound_ctrl:1
	v_fmac_f32_e32 v32, v27, v41
	v_fmac_f32_e32 v32, v17, v16
	v_add_f32_e32 v16, v45, v32
	v_mul_f32_e32 v13, v13, v21
	v_mul_f32_e32 v13, v16, v13
	v_cvt_pk_bf16_f32 v71, v9, v13
	s_and_saveexec_b64 s[56:57], s[2:3]
	s_xor_b64 s[56:57], exec, s[56:57]
	s_cbranch_execz .LBB0_1235
	v_mov_b64_e32 v[16:17], s[48:49]
	v_mad_i64_i32 v[16:17], s[58:59], v157, s85, v[16:17]
	v_lshl_add_u64 v[16:17], v[146:147], 1, v[16:17]
	v_mov_b32_e32 v232, v253
	v_mov_b32_e32 v233, v254
	v_mov_b32_e32 v234, v70
	v_mov_b32_e32 v235, v71
	s_nop 1
	v_permlane16_swap_b32_e32 v232, v234
	v_permlane16_swap_b32_e32 v233, v235
	v_lshl_add_u64 v[236:237], v[16:17], 0, v[238:239]
	global_store_dwordx4 v[236:237], v[232:235], off
	s_nop 1

	.amdhsa_kernel _Z8yoco_fwd4Args
		.amdhsa_group_segment_fixed_size 0
		.amdhsa_private_segment_fixed_size 0
		.amdhsa_kernarg_size 496
		.amdhsa_user_sgpr_count 2
		.amdhsa_user_sgpr_dispatch_ptr 0
		.amdhsa_user_sgpr_queue_ptr 0
		.amdhsa_user_sgpr_kernarg_segment_ptr 1
		.amdhsa_user_sgpr_dispatch_id 0
		.amdhsa_user_sgpr_kernarg_preload_length 0
		.amdhsa_user_sgpr_kernarg_preload_offset 0
		.amdhsa_user_sgpr_private_segment_size 0
		.amdhsa_uses_dynamic_stack 0
		.amdhsa_enable_private_segment 0
		.amdhsa_system_sgpr_workgroup_id_x 1
		.amdhsa_system_sgpr_workgroup_id_y 0
		.amdhsa_system_sgpr_workgroup_id_z 0
		.amdhsa_system_sgpr_workgroup_info 0
		.amdhsa_system_vgpr_workitem_id 2
		.amdhsa_next_free_vgpr 256
		.amdhsa_next_free_sgpr 102
		.amdhsa_accum_offset 256
		.amdhsa_reserve_vcc 1
		.amdhsa_float_round_mode_32 0
		.amdhsa_float_round_mode_16_64 0
		.amdhsa_float_denorm_mode_32 3
		.amdhsa_float_denorm_mode_16_64 3
		.amdhsa_dx10_clamp 1
		.amdhsa_ieee_mode 1
		.amdhsa_fp16_overflow 0
		.amdhsa_tg_split 0
		.amdhsa_exception_fp_ieee_invalid_op 0
		.amdhsa_exception_fp_denorm_src 0
		.amdhsa_exception_fp_ieee_div_zero 0
		.amdhsa_exception_fp_ieee_overflow 0
		.amdhsa_exception_fp_ieee_underflow 0
		.amdhsa_exception_fp_ieee_inexact 0
		.amdhsa_exception_int_div_zero 0
	.end_amdhsa_kernel

amdhsa.kernels:
  - .agpr_count:     0
    .args:
      - .offset:         0
        .size:           240
        .value_kind:     by_value
      - .offset:         240
        .size:           4
        .value_kind:     hidden_block_count_x
      - .offset:         244
        .size:           4
        .value_kind:     hidden_block_count_y
      - .offset:         248
        .size:           4
        .value_kind:     hidden_block_count_z
      - .offset:         252
        .size:           2
        .value_kind:     hidden_group_size_x
      - .offset:         254
        .size:           2
        .value_kind:     hidden_group_size_y
      - .offset:         256
        .size:           2
        .value_kind:     hidden_group_size_z
      - .offset:         258
        .size:           2
        .value_kind:     hidden_remainder_x
      - .offset:         260
        .size:           2
        .value_kind:     hidden_remainder_y
      - .offset:         262
        .size:           2
        .value_kind:     hidden_remainder_z
      - .offset:         280
        .size:           8
        .value_kind:     hidden_global_offset_x
      - .offset:         288
        .size:           8
        .value_kind:     hidden_global_offset_y
      - .offset:         296
        .size:           8
        .value_kind:     hidden_global_offset_z
      - .offset:         304
        .size:           2
        .value_kind:     hidden_grid_dims
      - .offset:         328
        .size:           8
        .value_kind:     hidden_multigrid_sync_arg
      - .offset:         360
        .size:           4
        .value_kind:     hidden_dynamic_lds_size
    .group_segment_fixed_size: 0
    .kernarg_segment_align: 8
    .kernarg_segment_size: 496
    .language:       OpenCL C
    .language_version:
      - 2
      - 0
    .max_flat_workgroup_size: 512
    .name:           _Z8yoco_fwd4Args
    .private_segment_fixed_size: 0
    .sgpr_count:     108
    .sgpr_spill_count: 7
    .symbol:         _Z8yoco_fwd4Args.kd
    .uniform_work_group_size: 1
    .uses_dynamic_stack: false
    .vgpr_count:     256
    .vgpr_spill_count: 0
    .wavefront_size: 64
